# P3 merge epilogue rewritten by hand: gate loads batched 16 in flight and refilled as 8-column blocks retire (was one load + vmcnt(0) per block); bit-identical arithmetic
# speedup vs baseline: 1.0147x; 1.0147x over previous
;     static __device__ __forceinline__ float e1(float x) { return 1.0f + __expf(-fminf(fmaxf(x, -60.f), 60.f)); }
;     __device__ __forceinline__ void operator()(f32x4 (&acc)[2][2][4][2], const Unit& u, int wr, int wc, int fr, int fq) const {
;         const int row0 = u.pm * BM + wr * 64 + fr, col0 = u.pn * BM + wc * 32 + 8 * fq;
; #pragma unroll
;         for (int ai = 0; ai < 2; ++ai)
; #pragma unroll
;             for (int m = 0; m < 4; ++m) {
;                 const int row = row0 + ai * HALF + m * 16;
; #pragma unroll
;                 for (int bj = 0; bj < 2; ++bj) {
;                     const int col = col0 + bj * HALF;
;                     const bf16_t* gp = proj + (size_t)row * NP + C_GATE + u.z * D + col;
;                     const u32x4 ga = *(const u32x4*)gp;
;                     float sc[8];
;                     { float a[8]; unpack8(ga, a);
; #pragma unroll
;                       for (int j = 0; j < 8; ++j) sc[j] = __builtin_amdgcn_rcpf(e1(a[j])); }
;                     if (u.z < 2) { const u32x4 gb = *(const u32x4*)(gp + D); float b[8]; unpack8(gb, b);
; #pragma unroll
;                       for (int j = 0; j < 8; ++j) sc[j] *= e1(b[j]); }
;                     f32x4 v0 = acc[ai][bj][m][0], v1 = acc[ai][bj][m][1];
;                     v0[0] *= sc[0]; v0[1] *= sc[1]; v0[2] *= sc[2]; v0[3] *= sc[3]; v1[0] *= sc[4]; v1[1] *= sc[5]; v1[2] *= sc[6]; v1[3] *= sc[7];
;                     if (u.z < 2) { acc[ai][bj][m][0] = v0; acc[ai][bj][m][1] = v1; }
.LBB0_622:
	v_lshl_add_u32 v152, s6, 8, v158
	v_lshl_or_b32 v2, s5, 8, v160
	v_mov_b64_e32 v[132:133], s[46:47]
	s_lshl_b32 s62, s4, 12
	s_add_u32 s62, s62, 0x6800
	s_mov_b32 s63, 0
	v_mad_i64_i32 v[132:133], s[6:7], v152, s25, v[132:133]
	v_ashrrev_i32_e32 v3, 31, v2
	v_lshl_add_u64 v[132:133], v[132:133], 0, s[62:63]
	v_ashrrev_i32_e32 v153, 31, v152
	v_lshlrev_b64 v[134:135], 12, v[152:153]
	v_lshl_add_u64 v[154:155], s[48:49], 0, v[134:135]
	v_lshl_add_u64 v[154:155], v[2:3], 1, v[154:155]
	v_lshl_add_u64 v[152:153], v[2:3], 1, v[132:133]
	s_cmp_lt_i32 s4, 2
	s_cbranch_scc0 .Lp3_store
	s_mov_b64 s[8:9], 0x0
	v_lshl_add_u64 v[156:157], v[152:153], 0, s[8:9]
	global_load_dwordx4 v[162:165], v[156:157], off offset:-4096
	global_load_dwordx4 v[166:169], v[156:157], off offset:0
	s_mov_b64 s[8:9], 0x0
	v_lshl_add_u64 v[156:157], v[152:153], 0, s[8:9]
	global_load_dwordx4 v[170:173], v[156:157], off offset:-3840
	global_load_dwordx4 v[174:177], v[156:157], off offset:256
	s_mov_b64 s[8:9], 0x88000
	v_lshl_add_u64 v[156:157], v[152:153], 0, s[8:9]
	global_load_dwordx4 v[178:181], v[156:157], off offset:-4096
	global_load_dwordx4 v[182:185], v[156:157], off offset:0
	s_mov_b64 s[8:9], 0x88000
	v_lshl_add_u64 v[156:157], v[152:153], 0, s[8:9]
	global_load_dwordx4 v[186:189], v[156:157], off offset:-3840
	global_load_dwordx4 v[190:193], v[156:157], off offset:256
	s_mov_b64 s[8:9], 0x110000
	v_lshl_add_u64 v[156:157], v[152:153], 0, s[8:9]
	global_load_dwordx4 v[194:197], v[156:157], off offset:-4096
	global_load_dwordx4 v[198:201], v[156:157], off offset:0
	s_mov_b64 s[8:9], 0x110000
	v_lshl_add_u64 v[156:157], v[152:153], 0, s[8:9]
	global_load_dwordx4 v[206:209], v[156:157], off offset:-3840
	global_load_dwordx4 v[210:213], v[156:157], off offset:256
	s_mov_b64 s[8:9], 0x198000
	v_lshl_add_u64 v[156:157], v[152:153], 0, s[8:9]
	global_load_dwordx4 v[228:231], v[156:157], off offset:-4096
	global_load_dwordx4 v[232:235], v[156:157], off offset:0
	s_mov_b64 s[8:9], 0x198000
	v_lshl_add_u64 v[156:157], v[152:153], 0, s[8:9]
	global_load_dwordx4 v[236:239], v[156:157], off offset:-3840
	global_load_dwordx4 v[240:243], v[156:157], off offset:256
	s_waitcnt vmcnt(14)
	v_lshlrev_b32_e32 v132, 16, v162
	v_and_b32_e32 v133, 0xffff0000, v162
	v_lshlrev_b32_e32 v134, 16, v163
	v_and_b32_e32 v135, 0xffff0000, v163
	v_lshlrev_b32_e32 v136, 16, v164
	v_and_b32_e32 v137, 0xffff0000, v164
	v_lshlrev_b32_e32 v138, 16, v165
	v_and_b32_e32 v139, 0xffff0000, v165
	v_lshlrev_b32_e32 v244, 16, v166
	v_and_b32_e32 v245, 0xffff0000, v166
	v_lshlrev_b32_e32 v246, 16, v167
	v_and_b32_e32 v247, 0xffff0000, v167
	v_lshlrev_b32_e32 v248, 16, v168
	v_and_b32_e32 v249, 0xffff0000, v168
	v_lshlrev_b32_e32 v250, 16, v169
	v_and_b32_e32 v251, 0xffff0000, v169
	s_mov_b64 s[8:9], 0x440000
	v_lshl_add_u64 v[156:157], v[152:153], 0, s[8:9]
	global_load_dwordx4 v[162:165], v[156:157], off offset:-4096
	global_load_dwordx4 v[166:169], v[156:157], off offset:0
	v_max_f32_e32 v132, v132, v132
	v_max_f32_e32 v133, v133, v133
	v_max_f32_e32 v134, v134, v134
	v_max_f32_e32 v135, v135, v135
	v_max_f32_e32 v136, v136, v136
	v_max_f32_e32 v137, v137, v137
	v_max_f32_e32 v138, v138, v138
	v_max_f32_e32 v139, v139, v139
	v_med3_f32 v132, v132, s97, v226
	v_med3_f32 v133, v133, s97, v226
	v_med3_f32 v134, v134, s97, v226
	v_med3_f32 v135, v135, s97, v226
	v_med3_f32 v136, v136, s97, v226
	v_med3_f32 v137, v137, s97, v226
	v_med3_f32 v138, v138, s97, v226
	v_med3_f32 v139, v139, s97, v226
	v_mul_f32_e32 v132, 0xbfb8aa3b, v132
	v_mul_f32_e32 v133, 0xbfb8aa3b, v133
	v_mul_f32_e32 v134, 0xbfb8aa3b, v134
	v_mul_f32_e32 v135, 0xbfb8aa3b, v135
	v_mul_f32_e32 v136, 0xbfb8aa3b, v136
	v_mul_f32_e32 v137, 0xbfb8aa3b, v137
	v_mul_f32_e32 v138, 0xbfb8aa3b, v138
	v_mul_f32_e32 v139, 0xbfb8aa3b, v139
	v_exp_f32_e32 v132, v132
	v_exp_f32_e32 v133, v133
	v_exp_f32_e32 v134, v134
	v_exp_f32_e32 v135, v135
	v_exp_f32_e32 v136, v136
	v_exp_f32_e32 v137, v137
	v_exp_f32_e32 v138, v138
	v_exp_f32_e32 v139, v139
	v_add_f32_e32 v132, 1.0, v132
	v_add_f32_e32 v133, 1.0, v133
	v_add_f32_e32 v134, 1.0, v134
	v_add_f32_e32 v135, 1.0, v135
	v_add_f32_e32 v136, 1.0, v136
	v_add_f32_e32 v137, 1.0, v137
	v_add_f32_e32 v138, 1.0, v138
	v_add_f32_e32 v139, 1.0, v139
	v_rcp_f32_e32 v132, v132
	v_rcp_f32_e32 v133, v133
	v_rcp_f32_e32 v134, v134
	v_rcp_f32_e32 v135, v135
	v_rcp_f32_e32 v136, v136
	v_rcp_f32_e32 v137, v137
	v_rcp_f32_e32 v138, v138
	v_rcp_f32_e32 v139, v139
	v_max_f32_e32 v244, v244, v244
	v_max_f32_e32 v245, v245, v245
	v_max_f32_e32 v246, v246, v246
	v_max_f32_e32 v247, v247, v247
	v_max_f32_e32 v248, v248, v248
	v_max_f32_e32 v249, v249, v249
	v_max_f32_e32 v250, v250, v250
	v_max_f32_e32 v251, v251, v251
	v_med3_f32 v244, v244, s97, v226
	v_med3_f32 v245, v245, s97, v226
	v_med3_f32 v246, v246, s97, v226
	v_med3_f32 v247, v247, s97, v226
	v_med3_f32 v248, v248, s97, v226
	v_med3_f32 v249, v249, s97, v226
	v_med3_f32 v250, v250, s97, v226
	v_med3_f32 v251, v251, s97, v226
	v_mul_f32_e32 v244, 0xbfb8aa3b, v244
	v_mul_f32_e32 v245, 0xbfb8aa3b, v245
	v_mul_f32_e32 v246, 0xbfb8aa3b, v246
	v_mul_f32_e32 v247, 0xbfb8aa3b, v247
	v_mul_f32_e32 v248, 0xbfb8aa3b, v248
	v_mul_f32_e32 v249, 0xbfb8aa3b, v249
	v_mul_f32_e32 v250, 0xbfb8aa3b, v250
	v_mul_f32_e32 v251, 0xbfb8aa3b, v251
	v_exp_f32_e32 v244, v244
	v_exp_f32_e32 v245, v245
	v_exp_f32_e32 v246, v246
	v_exp_f32_e32 v247, v247
	v_exp_f32_e32 v248, v248
	v_exp_f32_e32 v249, v249
	v_exp_f32_e32 v250, v250
	v_exp_f32_e32 v251, v251
	v_add_f32_e32 v244, 1.0, v244
	v_add_f32_e32 v245, 1.0, v245
	v_add_f32_e32 v246, 1.0, v246
	v_add_f32_e32 v247, 1.0, v247
	v_add_f32_e32 v248, 1.0, v248
	v_add_f32_e32 v249, 1.0, v249
	v_add_f32_e32 v250, 1.0, v250
	v_add_f32_e32 v251, 1.0, v251
	v_pk_mul_f32 v[132:133], v[132:133], v[244:245]
	v_pk_mul_f32 v[134:135], v[134:135], v[246:247]
	v_pk_mul_f32 v[136:137], v[136:137], v[248:249]
	v_pk_mul_f32 v[138:139], v[138:139], v[250:251]
	v_pk_mul_f32 v[128:129], v[128:129], v[132:133]
	v_pk_mul_f32 v[130:131], v[130:131], v[134:135]
	v_pk_mul_f32 v[124:125], v[124:125], v[136:137]
	v_pk_mul_f32 v[126:127], v[126:127], v[138:139]
	s_waitcnt vmcnt(14)
;     static __device__ __forceinline__ float e1(float x) { return 1.0f + __expf(-fminf(fmaxf(x, -60.f), 60.f)); }
;     __device__ __forceinline__ void operator()(f32x4 (&acc)[2][2][4][2], const Unit& u, int wr, int wc, int fr, int fq) const {
;     ...
;                     const int col = col0 + bj * HALF;
;                     const bf16_t* gp = proj + (size_t)row * NP + C_GATE + u.z * D + col;
;                     const u32x4 ga = *(const u32x4*)gp;
;                     float sc[8];
;                     { float a[8]; unpack8(ga, a);
; #pragma unroll
;                       for (int j = 0; j < 8; ++j) sc[j] = __builtin_amdgcn_rcpf(e1(a[j])); }
;                     if (u.z < 2) { const u32x4 gb = *(const u32x4*)(gp + D); float b[8]; unpack8(gb, b);
; #pragma unroll
;                       for (int j = 0; j < 8; ++j) sc[j] *= e1(b[j]); }
;                     f32x4 v0 = acc[ai][bj][m][0], v1 = acc[ai][bj][m][1];
;                     v0[0] *= sc[0]; v0[1] *= sc[1]; v0[2] *= sc[2]; v0[3] *= sc[3]; v1[0] *= sc[4]; v1[1] *= sc[5]; v1[2] *= sc[6]; v1[3] *= sc[7];
;                     if (u.z < 2) { acc[ai][bj][m][0] = v0; acc[ai][bj][m][1] = v1; }
	v_lshlrev_b32_e32 v132, 16, v170
	v_and_b32_e32 v133, 0xffff0000, v170
	v_lshlrev_b32_e32 v134, 16, v171
	v_and_b32_e32 v135, 0xffff0000, v171
	v_lshlrev_b32_e32 v136, 16, v172
	v_and_b32_e32 v137, 0xffff0000, v172
	v_lshlrev_b32_e32 v138, 16, v173
	v_and_b32_e32 v139, 0xffff0000, v173
	v_lshlrev_b32_e32 v244, 16, v174
	v_and_b32_e32 v245, 0xffff0000, v174
	v_lshlrev_b32_e32 v246, 16, v175
	v_and_b32_e32 v247, 0xffff0000, v175
	v_lshlrev_b32_e32 v248, 16, v176
	v_and_b32_e32 v249, 0xffff0000, v176
	v_lshlrev_b32_e32 v250, 16, v177
	v_and_b32_e32 v251, 0xffff0000, v177
	s_mov_b64 s[8:9], 0x440000
	v_lshl_add_u64 v[156:157], v[152:153], 0, s[8:9]
	global_load_dwordx4 v[170:173], v[156:157], off offset:-3840
	global_load_dwordx4 v[174:177], v[156:157], off offset:256
	v_max_f32_e32 v132, v132, v132
	v_max_f32_e32 v133, v133, v133
	v_max_f32_e32 v134, v134, v134
	v_max_f32_e32 v135, v135, v135
	v_max_f32_e32 v136, v136, v136
	v_max_f32_e32 v137, v137, v137
	v_max_f32_e32 v138, v138, v138
	v_max_f32_e32 v139, v139, v139
	v_med3_f32 v132, v132, s97, v226
	v_med3_f32 v133, v133, s97, v226
	v_med3_f32 v134, v134, s97, v226
	v_med3_f32 v135, v135, s97, v226
	v_med3_f32 v136, v136, s97, v226
	v_med3_f32 v137, v137, s97, v226
	v_med3_f32 v138, v138, s97, v226
	v_med3_f32 v139, v139, s97, v226
	v_mul_f32_e32 v132, 0xbfb8aa3b, v132
	v_mul_f32_e32 v133, 0xbfb8aa3b, v133
	v_mul_f32_e32 v134, 0xbfb8aa3b, v134
	v_mul_f32_e32 v135, 0xbfb8aa3b, v135
	v_mul_f32_e32 v136, 0xbfb8aa3b, v136
	v_mul_f32_e32 v137, 0xbfb8aa3b, v137
	v_mul_f32_e32 v138, 0xbfb8aa3b, v138
	v_mul_f32_e32 v139, 0xbfb8aa3b, v139
	v_exp_f32_e32 v132, v132
	v_exp_f32_e32 v133, v133
	v_exp_f32_e32 v134, v134
	v_exp_f32_e32 v135, v135
	v_exp_f32_e32 v136, v136
	v_exp_f32_e32 v137, v137
	v_exp_f32_e32 v138, v138
	v_exp_f32_e32 v139, v139
	v_add_f32_e32 v132, 1.0, v132
	v_add_f32_e32 v133, 1.0, v133
	v_add_f32_e32 v134, 1.0, v134
	v_add_f32_e32 v135, 1.0, v135
	v_add_f32_e32 v136, 1.0, v136
	v_add_f32_e32 v137, 1.0, v137
	v_add_f32_e32 v138, 1.0, v138
	v_add_f32_e32 v139, 1.0, v139
	v_rcp_f32_e32 v132, v132
	v_rcp_f32_e32 v133, v133
	v_rcp_f32_e32 v134, v134
	v_rcp_f32_e32 v135, v135
	v_rcp_f32_e32 v136, v136
	v_rcp_f32_e32 v137, v137
	v_rcp_f32_e32 v138, v138
	v_rcp_f32_e32 v139, v139
	v_max_f32_e32 v244, v244, v244
	v_max_f32_e32 v245, v245, v245
	v_max_f32_e32 v246, v246, v246
	v_max_f32_e32 v247, v247, v247
	v_max_f32_e32 v248, v248, v248
	v_max_f32_e32 v249, v249, v249
	v_max_f32_e32 v250, v250, v250
	v_max_f32_e32 v251, v251, v251
	v_med3_f32 v244, v244, s97, v226
	v_med3_f32 v245, v245, s97, v226
	v_med3_f32 v246, v246, s97, v226
	v_med3_f32 v247, v247, s97, v226
	v_med3_f32 v248, v248, s97, v226
	v_med3_f32 v249, v249, s97, v226
	v_med3_f32 v250, v250, s97, v226
	v_med3_f32 v251, v251, s97, v226
	v_mul_f32_e32 v244, 0xbfb8aa3b, v244
	v_mul_f32_e32 v245, 0xbfb8aa3b, v245
	v_mul_f32_e32 v246, 0xbfb8aa3b, v246
	v_mul_f32_e32 v247, 0xbfb8aa3b, v247
	v_mul_f32_e32 v248, 0xbfb8aa3b, v248
	v_mul_f32_e32 v249, 0xbfb8aa3b, v249
	v_mul_f32_e32 v250, 0xbfb8aa3b, v250
	v_mul_f32_e32 v251, 0xbfb8aa3b, v251
	v_exp_f32_e32 v244, v244
	v_exp_f32_e32 v245, v245
	v_exp_f32_e32 v246, v246
	v_exp_f32_e32 v247, v247
	v_exp_f32_e32 v248, v248
	v_exp_f32_e32 v249, v249
	v_exp_f32_e32 v250, v250
	v_exp_f32_e32 v251, v251
	v_add_f32_e32 v244, 1.0, v244
	v_add_f32_e32 v245, 1.0, v245
	v_add_f32_e32 v246, 1.0, v246
	v_add_f32_e32 v247, 1.0, v247
	v_add_f32_e32 v248, 1.0, v248
	v_add_f32_e32 v249, 1.0, v249
	v_add_f32_e32 v250, 1.0, v250
	v_add_f32_e32 v251, 1.0, v251
	v_pk_mul_f32 v[132:133], v[132:133], v[244:245]
	v_pk_mul_f32 v[134:135], v[134:135], v[246:247]
	v_pk_mul_f32 v[136:137], v[136:137], v[248:249]
	v_pk_mul_f32 v[138:139], v[138:139], v[250:251]
	v_pk_mul_f32 v[96:97], v[96:97], v[132:133]
	v_pk_mul_f32 v[98:99], v[98:99], v[134:135]
	v_pk_mul_f32 v[92:93], v[92:93], v[136:137]
	v_pk_mul_f32 v[94:95], v[94:95], v[138:139]
	s_waitcnt vmcnt(14)
	v_lshlrev_b32_e32 v132, 16, v178
	v_and_b32_e32 v133, 0xffff0000, v178
	v_lshlrev_b32_e32 v134, 16, v179
	v_and_b32_e32 v135, 0xffff0000, v179
	v_lshlrev_b32_e32 v136, 16, v180
	v_and_b32_e32 v137, 0xffff0000, v180
	v_lshlrev_b32_e32 v138, 16, v181
	v_and_b32_e32 v139, 0xffff0000, v181
	v_lshlrev_b32_e32 v244, 16, v182
	v_and_b32_e32 v245, 0xffff0000, v182
	v_lshlrev_b32_e32 v246, 16, v183
	v_and_b32_e32 v247, 0xffff0000, v183
	v_lshlrev_b32_e32 v248, 16, v184
	v_and_b32_e32 v249, 0xffff0000, v184
	v_lshlrev_b32_e32 v250, 16, v185
	v_and_b32_e32 v251, 0xffff0000, v185
	s_mov_b64 s[8:9], 0x4c8000
	v_lshl_add_u64 v[156:157], v[152:153], 0, s[8:9]
	global_load_dwordx4 v[178:181], v[156:157], off offset:-4096
	global_load_dwordx4 v[182:185], v[156:157], off offset:0
	v_max_f32_e32 v132, v132, v132
	v_max_f32_e32 v133, v133, v133
	v_max_f32_e32 v134, v134, v134
	v_max_f32_e32 v135, v135, v135
	v_max_f32_e32 v136, v136, v136
	v_max_f32_e32 v137, v137, v137
	v_max_f32_e32 v138, v138, v138
	v_max_f32_e32 v139, v139, v139
	v_med3_f32 v132, v132, s97, v226
	v_med3_f32 v133, v133, s97, v226
	v_med3_f32 v134, v134, s97, v226
	v_med3_f32 v135, v135, s97, v226
	v_med3_f32 v136, v136, s97, v226
	v_med3_f32 v137, v137, s97, v226
	v_med3_f32 v138, v138, s97, v226
	v_med3_f32 v139, v139, s97, v226
	v_mul_f32_e32 v132, 0xbfb8aa3b, v132
	v_mul_f32_e32 v133, 0xbfb8aa3b, v133
	v_mul_f32_e32 v134, 0xbfb8aa3b, v134
	v_mul_f32_e32 v135, 0xbfb8aa3b, v135
	v_mul_f32_e32 v136, 0xbfb8aa3b, v136
	v_mul_f32_e32 v137, 0xbfb8aa3b, v137
	v_mul_f32_e32 v138, 0xbfb8aa3b, v138
	v_mul_f32_e32 v139, 0xbfb8aa3b, v139
	v_exp_f32_e32 v132, v132
	v_exp_f32_e32 v133, v133
	v_exp_f32_e32 v134, v134
;     static __device__ __forceinline__ float e1(float x) { return 1.0f + __expf(-fminf(fmaxf(x, -60.f), 60.f)); }
;     __device__ __forceinline__ void operator()(f32x4 (&acc)[2][2][4][2], const Unit& u, int wr, int wc, int fr, int fq) const {
;     ...
;                     const int col = col0 + bj * HALF;
;                     const bf16_t* gp = proj + (size_t)row * NP + C_GATE + u.z * D + col;
;                     const u32x4 ga = *(const u32x4*)gp;
;                     float sc[8];
;                     { float a[8]; unpack8(ga, a);
; #pragma unroll
;                       for (int j = 0; j < 8; ++j) sc[j] = __builtin_amdgcn_rcpf(e1(a[j])); }
;                     if (u.z < 2) { const u32x4 gb = *(const u32x4*)(gp + D); float b[8]; unpack8(gb, b);
; #pragma unroll
;                       for (int j = 0; j < 8; ++j) sc[j] *= e1(b[j]); }
;                     f32x4 v0 = acc[ai][bj][m][0], v1 = acc[ai][bj][m][1];
;                     v0[0] *= sc[0]; v0[1] *= sc[1]; v0[2] *= sc[2]; v0[3] *= sc[3]; v1[0] *= sc[4]; v1[1] *= sc[5]; v1[2] *= sc[6]; v1[3] *= sc[7];
;                     if (u.z < 2) { acc[ai][bj][m][0] = v0; acc[ai][bj][m][1] = v1; }
	v_exp_f32_e32 v135, v135
	v_exp_f32_e32 v136, v136
	v_exp_f32_e32 v137, v137
	v_exp_f32_e32 v138, v138
	v_exp_f32_e32 v139, v139
	v_add_f32_e32 v132, 1.0, v132
	v_add_f32_e32 v133, 1.0, v133
	v_add_f32_e32 v134, 1.0, v134
	v_add_f32_e32 v135, 1.0, v135
	v_add_f32_e32 v136, 1.0, v136
	v_add_f32_e32 v137, 1.0, v137
	v_add_f32_e32 v138, 1.0, v138
	v_add_f32_e32 v139, 1.0, v139
	v_rcp_f32_e32 v132, v132
	v_rcp_f32_e32 v133, v133
	v_rcp_f32_e32 v134, v134
	v_rcp_f32_e32 v135, v135
	v_rcp_f32_e32 v136, v136
	v_rcp_f32_e32 v137, v137
	v_rcp_f32_e32 v138, v138
	v_rcp_f32_e32 v139, v139
	v_max_f32_e32 v244, v244, v244
	v_max_f32_e32 v245, v245, v245
	v_max_f32_e32 v246, v246, v246
	v_max_f32_e32 v247, v247, v247
	v_max_f32_e32 v248, v248, v248
	v_max_f32_e32 v249, v249, v249
	v_max_f32_e32 v250, v250, v250
	v_max_f32_e32 v251, v251, v251
	v_med3_f32 v244, v244, s97, v226
	v_med3_f32 v245, v245, s97, v226
	v_med3_f32 v246, v246, s97, v226
	v_med3_f32 v247, v247, s97, v226
	v_med3_f32 v248, v248, s97, v226
	v_med3_f32 v249, v249, s97, v226
	v_med3_f32 v250, v250, s97, v226
	v_med3_f32 v251, v251, s97, v226
	v_mul_f32_e32 v244, 0xbfb8aa3b, v244
	v_mul_f32_e32 v245, 0xbfb8aa3b, v245
	v_mul_f32_e32 v246, 0xbfb8aa3b, v246
	v_mul_f32_e32 v247, 0xbfb8aa3b, v247
	v_mul_f32_e32 v248, 0xbfb8aa3b, v248
	v_mul_f32_e32 v249, 0xbfb8aa3b, v249
	v_mul_f32_e32 v250, 0xbfb8aa3b, v250
	v_mul_f32_e32 v251, 0xbfb8aa3b, v251
	v_exp_f32_e32 v244, v244
	v_exp_f32_e32 v245, v245
	v_exp_f32_e32 v246, v246
	v_exp_f32_e32 v247, v247
	v_exp_f32_e32 v248, v248
	v_exp_f32_e32 v249, v249
	v_exp_f32_e32 v250, v250
	v_exp_f32_e32 v251, v251
	v_add_f32_e32 v244, 1.0, v244
	v_add_f32_e32 v245, 1.0, v245
	v_add_f32_e32 v246, 1.0, v246
	v_add_f32_e32 v247, 1.0, v247
	v_add_f32_e32 v248, 1.0, v248
	v_add_f32_e32 v249, 1.0, v249
	v_add_f32_e32 v250, 1.0, v250
	v_add_f32_e32 v251, 1.0, v251
	v_pk_mul_f32 v[132:133], v[132:133], v[244:245]
	v_pk_mul_f32 v[134:135], v[134:135], v[246:247]
	v_pk_mul_f32 v[136:137], v[136:137], v[248:249]
	v_pk_mul_f32 v[138:139], v[138:139], v[250:251]
	v_pk_mul_f32 v[120:121], v[120:121], v[132:133]
	v_pk_mul_f32 v[122:123], v[122:123], v[134:135]
	v_pk_mul_f32 v[116:117], v[116:117], v[136:137]
	v_pk_mul_f32 v[118:119], v[118:119], v[138:139]
	s_waitcnt vmcnt(14)
	v_lshlrev_b32_e32 v132, 16, v186
	v_and_b32_e32 v133, 0xffff0000, v186
	v_lshlrev_b32_e32 v134, 16, v187
	v_and_b32_e32 v135, 0xffff0000, v187
	v_lshlrev_b32_e32 v136, 16, v188
	v_and_b32_e32 v137, 0xffff0000, v188
	v_lshlrev_b32_e32 v138, 16, v189
	v_and_b32_e32 v139, 0xffff0000, v189
	v_lshlrev_b32_e32 v244, 16, v190
	v_and_b32_e32 v245, 0xffff0000, v190
	v_lshlrev_b32_e32 v246, 16, v191
	v_and_b32_e32 v247, 0xffff0000, v191
	v_lshlrev_b32_e32 v248, 16, v192
	v_and_b32_e32 v249, 0xffff0000, v192
	v_lshlrev_b32_e32 v250, 16, v193
	v_and_b32_e32 v251, 0xffff0000, v193
	s_mov_b64 s[8:9], 0x4c8000
	v_lshl_add_u64 v[156:157], v[152:153], 0, s[8:9]
	global_load_dwordx4 v[186:189], v[156:157], off offset:-3840
	global_load_dwordx4 v[190:193], v[156:157], off offset:256
	v_max_f32_e32 v132, v132, v132
	v_max_f32_e32 v133, v133, v133
	v_max_f32_e32 v134, v134, v134
	v_max_f32_e32 v135, v135, v135
	v_max_f32_e32 v136, v136, v136
	v_max_f32_e32 v137, v137, v137
	v_max_f32_e32 v138, v138, v138
	v_max_f32_e32 v139, v139, v139
	v_med3_f32 v132, v132, s97, v226
	v_med3_f32 v133, v133, s97, v226
	v_med3_f32 v134, v134, s97, v226
	v_med3_f32 v135, v135, s97, v226
	v_med3_f32 v136, v136, s97, v226
	v_med3_f32 v137, v137, s97, v226
	v_med3_f32 v138, v138, s97, v226
	v_med3_f32 v139, v139, s97, v226
	v_mul_f32_e32 v132, 0xbfb8aa3b, v132
	v_mul_f32_e32 v133, 0xbfb8aa3b, v133
	v_mul_f32_e32 v134, 0xbfb8aa3b, v134
	v_mul_f32_e32 v135, 0xbfb8aa3b, v135
	v_mul_f32_e32 v136, 0xbfb8aa3b, v136
	v_mul_f32_e32 v137, 0xbfb8aa3b, v137
	v_mul_f32_e32 v138, 0xbfb8aa3b, v138
	v_mul_f32_e32 v139, 0xbfb8aa3b, v139
	v_exp_f32_e32 v132, v132
	v_exp_f32_e32 v133, v133
	v_exp_f32_e32 v134, v134
	v_exp_f32_e32 v135, v135
	v_exp_f32_e32 v136, v136
	v_exp_f32_e32 v137, v137
	v_exp_f32_e32 v138, v138
	v_exp_f32_e32 v139, v139
	v_add_f32_e32 v132, 1.0, v132
	v_add_f32_e32 v133, 1.0, v133
	v_add_f32_e32 v134, 1.0, v134
	v_add_f32_e32 v135, 1.0, v135
	v_add_f32_e32 v136, 1.0, v136
	v_add_f32_e32 v137, 1.0, v137
	v_add_f32_e32 v138, 1.0, v138
	v_add_f32_e32 v139, 1.0, v139
	v_rcp_f32_e32 v132, v132
	v_rcp_f32_e32 v133, v133
	v_rcp_f32_e32 v134, v134
	v_rcp_f32_e32 v135, v135
	v_rcp_f32_e32 v136, v136
	v_rcp_f32_e32 v137, v137
	v_rcp_f32_e32 v138, v138
	v_rcp_f32_e32 v139, v139
	v_max_f32_e32 v244, v244, v244
	v_max_f32_e32 v245, v245, v245
	v_max_f32_e32 v246, v246, v246
	v_max_f32_e32 v247, v247, v247
	v_max_f32_e32 v248, v248, v248
	v_max_f32_e32 v249, v249, v249
	v_max_f32_e32 v250, v250, v250
	v_max_f32_e32 v251, v251, v251
	v_med3_f32 v244, v244, s97, v226
	v_med3_f32 v245, v245, s97, v226
	v_med3_f32 v246, v246, s97, v226
	v_med3_f32 v247, v247, s97, v226
	v_med3_f32 v248, v248, s97, v226
	v_med3_f32 v249, v249, s97, v226
	v_med3_f32 v250, v250, s97, v226
	v_med3_f32 v251, v251, s97, v226
	v_mul_f32_e32 v244, 0xbfb8aa3b, v244
	v_mul_f32_e32 v245, 0xbfb8aa3b, v245
	v_mul_f32_e32 v246, 0xbfb8aa3b, v246
	v_mul_f32_e32 v247, 0xbfb8aa3b, v247
	v_mul_f32_e32 v248, 0xbfb8aa3b, v248
	v_mul_f32_e32 v249, 0xbfb8aa3b, v249
	v_mul_f32_e32 v250, 0xbfb8aa3b, v250
	v_mul_f32_e32 v251, 0xbfb8aa3b, v251
	v_exp_f32_e32 v244, v244
	v_exp_f32_e32 v245, v245
	v_exp_f32_e32 v246, v246
	v_exp_f32_e32 v247, v247
	v_exp_f32_e32 v248, v248
	v_exp_f32_e32 v249, v249
	v_exp_f32_e32 v250, v250
	v_exp_f32_e32 v251, v251
	v_add_f32_e32 v244, 1.0, v244
	v_add_f32_e32 v245, 1.0, v245
	v_add_f32_e32 v246, 1.0, v246
	v_add_f32_e32 v247, 1.0, v247
	v_add_f32_e32 v248, 1.0, v248
	v_add_f32_e32 v249, 1.0, v249
	v_add_f32_e32 v250, 1.0, v250
	v_add_f32_e32 v251, 1.0, v251
	v_pk_mul_f32 v[132:133], v[132:133], v[244:245]
	v_pk_mul_f32 v[134:135], v[134:135], v[246:247]
	v_pk_mul_f32 v[136:137], v[136:137], v[248:249]
	v_pk_mul_f32 v[138:139], v[138:139], v[250:251]
	v_pk_mul_f32 v[88:89], v[88:89], v[132:133]
	v_pk_mul_f32 v[90:91], v[90:91], v[134:135]
	v_pk_mul_f32 v[84:85], v[84:85], v[136:137]
	v_pk_mul_f32 v[86:87], v[86:87], v[138:139]
	s_waitcnt vmcnt(14)
;     static __device__ __forceinline__ float e1(float x) { return 1.0f + __expf(-fminf(fmaxf(x, -60.f), 60.f)); }
;     __device__ __forceinline__ void operator()(f32x4 (&acc)[2][2][4][2], const Unit& u, int wr, int wc, int fr, int fq) const {
;     ...
;                     const int col = col0 + bj * HALF;
;                     const bf16_t* gp = proj + (size_t)row * NP + C_GATE + u.z * D + col;
;                     const u32x4 ga = *(const u32x4*)gp;
;                     float sc[8];
;                     { float a[8]; unpack8(ga, a);
; #pragma unroll
;                       for (int j = 0; j < 8; ++j) sc[j] = __builtin_amdgcn_rcpf(e1(a[j])); }
;                     if (u.z < 2) { const u32x4 gb = *(const u32x4*)(gp + D); float b[8]; unpack8(gb, b);
; #pragma unroll
;                       for (int j = 0; j < 8; ++j) sc[j] *= e1(b[j]); }
;                     f32x4 v0 = acc[ai][bj][m][0], v1 = acc[ai][bj][m][1];
;                     v0[0] *= sc[0]; v0[1] *= sc[1]; v0[2] *= sc[2]; v0[3] *= sc[3]; v1[0] *= sc[4]; v1[1] *= sc[5]; v1[2] *= sc[6]; v1[3] *= sc[7];
;                     if (u.z < 2) { acc[ai][bj][m][0] = v0; acc[ai][bj][m][1] = v1; }
	v_lshlrev_b32_e32 v132, 16, v194
	v_and_b32_e32 v133, 0xffff0000, v194
	v_lshlrev_b32_e32 v134, 16, v195
	v_and_b32_e32 v135, 0xffff0000, v195
	v_lshlrev_b32_e32 v136, 16, v196
	v_and_b32_e32 v137, 0xffff0000, v196
	v_lshlrev_b32_e32 v138, 16, v197
	v_and_b32_e32 v139, 0xffff0000, v197
	v_lshlrev_b32_e32 v244, 16, v198
	v_and_b32_e32 v245, 0xffff0000, v198
	v_lshlrev_b32_e32 v246, 16, v199
	v_and_b32_e32 v247, 0xffff0000, v199
	v_lshlrev_b32_e32 v248, 16, v200
	v_and_b32_e32 v249, 0xffff0000, v200
	v_lshlrev_b32_e32 v250, 16, v201
	v_and_b32_e32 v251, 0xffff0000, v201
	s_mov_b64 s[8:9], 0x550000
	v_lshl_add_u64 v[156:157], v[152:153], 0, s[8:9]
	global_load_dwordx4 v[194:197], v[156:157], off offset:-4096
	global_load_dwordx4 v[198:201], v[156:157], off offset:0
	v_max_f32_e32 v132, v132, v132
	v_max_f32_e32 v133, v133, v133
	v_max_f32_e32 v134, v134, v134
	v_max_f32_e32 v135, v135, v135
	v_max_f32_e32 v136, v136, v136
	v_max_f32_e32 v137, v137, v137
	v_max_f32_e32 v138, v138, v138
	v_max_f32_e32 v139, v139, v139
	v_med3_f32 v132, v132, s97, v226
	v_med3_f32 v133, v133, s97, v226
	v_med3_f32 v134, v134, s97, v226
	v_med3_f32 v135, v135, s97, v226
	v_med3_f32 v136, v136, s97, v226
	v_med3_f32 v137, v137, s97, v226
	v_med3_f32 v138, v138, s97, v226
	v_med3_f32 v139, v139, s97, v226
	v_mul_f32_e32 v132, 0xbfb8aa3b, v132
	v_mul_f32_e32 v133, 0xbfb8aa3b, v133
	v_mul_f32_e32 v134, 0xbfb8aa3b, v134
	v_mul_f32_e32 v135, 0xbfb8aa3b, v135
	v_mul_f32_e32 v136, 0xbfb8aa3b, v136
	v_mul_f32_e32 v137, 0xbfb8aa3b, v137
	v_mul_f32_e32 v138, 0xbfb8aa3b, v138
	v_mul_f32_e32 v139, 0xbfb8aa3b, v139
	v_exp_f32_e32 v132, v132
	v_exp_f32_e32 v133, v133
	v_exp_f32_e32 v134, v134
	v_exp_f32_e32 v135, v135
	v_exp_f32_e32 v136, v136
	v_exp_f32_e32 v137, v137
	v_exp_f32_e32 v138, v138
	v_exp_f32_e32 v139, v139
	v_add_f32_e32 v132, 1.0, v132
	v_add_f32_e32 v133, 1.0, v133
	v_add_f32_e32 v134, 1.0, v134
	v_add_f32_e32 v135, 1.0, v135
	v_add_f32_e32 v136, 1.0, v136
	v_add_f32_e32 v137, 1.0, v137
	v_add_f32_e32 v138, 1.0, v138
	v_add_f32_e32 v139, 1.0, v139
	v_rcp_f32_e32 v132, v132
	v_rcp_f32_e32 v133, v133
	v_rcp_f32_e32 v134, v134
	v_rcp_f32_e32 v135, v135
	v_rcp_f32_e32 v136, v136
	v_rcp_f32_e32 v137, v137
	v_rcp_f32_e32 v138, v138
	v_rcp_f32_e32 v139, v139
	v_max_f32_e32 v244, v244, v244
	v_max_f32_e32 v245, v245, v245
	v_max_f32_e32 v246, v246, v246
	v_max_f32_e32 v247, v247, v247
	v_max_f32_e32 v248, v248, v248
	v_max_f32_e32 v249, v249, v249
	v_max_f32_e32 v250, v250, v250
	v_max_f32_e32 v251, v251, v251
	v_med3_f32 v244, v244, s97, v226
	v_med3_f32 v245, v245, s97, v226
	v_med3_f32 v246, v246, s97, v226
	v_med3_f32 v247, v247, s97, v226
	v_med3_f32 v248, v248, s97, v226
	v_med3_f32 v249, v249, s97, v226
	v_med3_f32 v250, v250, s97, v226
	v_med3_f32 v251, v251, s97, v226
	v_mul_f32_e32 v244, 0xbfb8aa3b, v244
	v_mul_f32_e32 v245, 0xbfb8aa3b, v245
	v_mul_f32_e32 v246, 0xbfb8aa3b, v246
	v_mul_f32_e32 v247, 0xbfb8aa3b, v247
	v_mul_f32_e32 v248, 0xbfb8aa3b, v248
	v_mul_f32_e32 v249, 0xbfb8aa3b, v249
	v_mul_f32_e32 v250, 0xbfb8aa3b, v250
	v_mul_f32_e32 v251, 0xbfb8aa3b, v251
	v_exp_f32_e32 v244, v244
	v_exp_f32_e32 v245, v245
	v_exp_f32_e32 v246, v246
	v_exp_f32_e32 v247, v247
	v_exp_f32_e32 v248, v248
	v_exp_f32_e32 v249, v249
	v_exp_f32_e32 v250, v250
	v_exp_f32_e32 v251, v251
	v_add_f32_e32 v244, 1.0, v244
	v_add_f32_e32 v245, 1.0, v245
	v_add_f32_e32 v246, 1.0, v246
	v_add_f32_e32 v247, 1.0, v247
	v_add_f32_e32 v248, 1.0, v248
	v_add_f32_e32 v249, 1.0, v249
	v_add_f32_e32 v250, 1.0, v250
	v_add_f32_e32 v251, 1.0, v251
	v_pk_mul_f32 v[132:133], v[132:133], v[244:245]
	v_pk_mul_f32 v[134:135], v[134:135], v[246:247]
	v_pk_mul_f32 v[136:137], v[136:137], v[248:249]
	v_pk_mul_f32 v[138:139], v[138:139], v[250:251]
	v_pk_mul_f32 v[112:113], v[112:113], v[132:133]
	v_pk_mul_f32 v[114:115], v[114:115], v[134:135]
	v_pk_mul_f32 v[108:109], v[108:109], v[136:137]
	v_pk_mul_f32 v[110:111], v[110:111], v[138:139]
	s_waitcnt vmcnt(14)
	v_lshlrev_b32_e32 v132, 16, v206
	v_and_b32_e32 v133, 0xffff0000, v206
	v_lshlrev_b32_e32 v134, 16, v207
	v_and_b32_e32 v135, 0xffff0000, v207
	v_lshlrev_b32_e32 v136, 16, v208
	v_and_b32_e32 v137, 0xffff0000, v208
	v_lshlrev_b32_e32 v138, 16, v209
	v_and_b32_e32 v139, 0xffff0000, v209
	v_lshlrev_b32_e32 v244, 16, v210
	v_and_b32_e32 v245, 0xffff0000, v210
	v_lshlrev_b32_e32 v246, 16, v211
	v_and_b32_e32 v247, 0xffff0000, v211
	v_lshlrev_b32_e32 v248, 16, v212
	v_and_b32_e32 v249, 0xffff0000, v212
	v_lshlrev_b32_e32 v250, 16, v213
	v_and_b32_e32 v251, 0xffff0000, v213
	s_mov_b64 s[8:9], 0x550000
	v_lshl_add_u64 v[156:157], v[152:153], 0, s[8:9]
	global_load_dwordx4 v[206:209], v[156:157], off offset:-3840
	global_load_dwordx4 v[210:213], v[156:157], off offset:256
	v_max_f32_e32 v132, v132, v132
	v_max_f32_e32 v133, v133, v133
	v_max_f32_e32 v134, v134, v134
	v_max_f32_e32 v135, v135, v135
	v_max_f32_e32 v136, v136, v136
	v_max_f32_e32 v137, v137, v137
	v_max_f32_e32 v138, v138, v138
	v_max_f32_e32 v139, v139, v139
	v_med3_f32 v132, v132, s97, v226
	v_med3_f32 v133, v133, s97, v226
	v_med3_f32 v134, v134, s97, v226
	v_med3_f32 v135, v135, s97, v226
	v_med3_f32 v136, v136, s97, v226
	v_med3_f32 v137, v137, s97, v226
	v_med3_f32 v138, v138, s97, v226
	v_med3_f32 v139, v139, s97, v226
	v_mul_f32_e32 v132, 0xbfb8aa3b, v132
	v_mul_f32_e32 v133, 0xbfb8aa3b, v133
	v_mul_f32_e32 v134, 0xbfb8aa3b, v134
	v_mul_f32_e32 v135, 0xbfb8aa3b, v135
	v_mul_f32_e32 v136, 0xbfb8aa3b, v136
	v_mul_f32_e32 v137, 0xbfb8aa3b, v137
	v_mul_f32_e32 v138, 0xbfb8aa3b, v138
	v_mul_f32_e32 v139, 0xbfb8aa3b, v139
	v_exp_f32_e32 v132, v132
	v_exp_f32_e32 v133, v133
;     static __device__ __forceinline__ float e1(float x) { return 1.0f + __expf(-fminf(fmaxf(x, -60.f), 60.f)); }
;     __device__ __forceinline__ void operator()(f32x4 (&acc)[2][2][4][2], const Unit& u, int wr, int wc, int fr, int fq) const {
;     ...
;                     const int col = col0 + bj * HALF;
;                     const bf16_t* gp = proj + (size_t)row * NP + C_GATE + u.z * D + col;
;                     const u32x4 ga = *(const u32x4*)gp;
;                     float sc[8];
;                     { float a[8]; unpack8(ga, a);
; #pragma unroll
;                       for (int j = 0; j < 8; ++j) sc[j] = __builtin_amdgcn_rcpf(e1(a[j])); }
;                     if (u.z < 2) { const u32x4 gb = *(const u32x4*)(gp + D); float b[8]; unpack8(gb, b);
; #pragma unroll
;                       for (int j = 0; j < 8; ++j) sc[j] *= e1(b[j]); }
;                     f32x4 v0 = acc[ai][bj][m][0], v1 = acc[ai][bj][m][1];
;                     v0[0] *= sc[0]; v0[1] *= sc[1]; v0[2] *= sc[2]; v0[3] *= sc[3]; v1[0] *= sc[4]; v1[1] *= sc[5]; v1[2] *= sc[6]; v1[3] *= sc[7];
;                     if (u.z < 2) { acc[ai][bj][m][0] = v0; acc[ai][bj][m][1] = v1; }
	v_exp_f32_e32 v134, v134
	v_exp_f32_e32 v135, v135
	v_exp_f32_e32 v136, v136
	v_exp_f32_e32 v137, v137
	v_exp_f32_e32 v138, v138
	v_exp_f32_e32 v139, v139
	v_add_f32_e32 v132, 1.0, v132
	v_add_f32_e32 v133, 1.0, v133
	v_add_f32_e32 v134, 1.0, v134
	v_add_f32_e32 v135, 1.0, v135
	v_add_f32_e32 v136, 1.0, v136
	v_add_f32_e32 v137, 1.0, v137
	v_add_f32_e32 v138, 1.0, v138
	v_add_f32_e32 v139, 1.0, v139
	v_rcp_f32_e32 v132, v132
	v_rcp_f32_e32 v133, v133
	v_rcp_f32_e32 v134, v134
	v_rcp_f32_e32 v135, v135
	v_rcp_f32_e32 v136, v136
	v_rcp_f32_e32 v137, v137
	v_rcp_f32_e32 v138, v138
	v_rcp_f32_e32 v139, v139
	v_max_f32_e32 v244, v244, v244
	v_max_f32_e32 v245, v245, v245
	v_max_f32_e32 v246, v246, v246
	v_max_f32_e32 v247, v247, v247
	v_max_f32_e32 v248, v248, v248
	v_max_f32_e32 v249, v249, v249
	v_max_f32_e32 v250, v250, v250
	v_max_f32_e32 v251, v251, v251
	v_med3_f32 v244, v244, s97, v226
	v_med3_f32 v245, v245, s97, v226
	v_med3_f32 v246, v246, s97, v226
	v_med3_f32 v247, v247, s97, v226
	v_med3_f32 v248, v248, s97, v226
	v_med3_f32 v249, v249, s97, v226
	v_med3_f32 v250, v250, s97, v226
	v_med3_f32 v251, v251, s97, v226
	v_mul_f32_e32 v244, 0xbfb8aa3b, v244
	v_mul_f32_e32 v245, 0xbfb8aa3b, v245
	v_mul_f32_e32 v246, 0xbfb8aa3b, v246
	v_mul_f32_e32 v247, 0xbfb8aa3b, v247
	v_mul_f32_e32 v248, 0xbfb8aa3b, v248
	v_mul_f32_e32 v249, 0xbfb8aa3b, v249
	v_mul_f32_e32 v250, 0xbfb8aa3b, v250
	v_mul_f32_e32 v251, 0xbfb8aa3b, v251
	v_exp_f32_e32 v244, v244
	v_exp_f32_e32 v245, v245
	v_exp_f32_e32 v246, v246
	v_exp_f32_e32 v247, v247
	v_exp_f32_e32 v248, v248
	v_exp_f32_e32 v249, v249
	v_exp_f32_e32 v250, v250
	v_exp_f32_e32 v251, v251
	v_add_f32_e32 v244, 1.0, v244
	v_add_f32_e32 v245, 1.0, v245
	v_add_f32_e32 v246, 1.0, v246
	v_add_f32_e32 v247, 1.0, v247
	v_add_f32_e32 v248, 1.0, v248
	v_add_f32_e32 v249, 1.0, v249
	v_add_f32_e32 v250, 1.0, v250
	v_add_f32_e32 v251, 1.0, v251
	v_pk_mul_f32 v[132:133], v[132:133], v[244:245]
	v_pk_mul_f32 v[134:135], v[134:135], v[246:247]
	v_pk_mul_f32 v[136:137], v[136:137], v[248:249]
	v_pk_mul_f32 v[138:139], v[138:139], v[250:251]
	v_pk_mul_f32 v[80:81], v[80:81], v[132:133]
	v_pk_mul_f32 v[82:83], v[82:83], v[134:135]
	v_pk_mul_f32 v[76:77], v[76:77], v[136:137]
	v_pk_mul_f32 v[78:79], v[78:79], v[138:139]
	s_waitcnt vmcnt(14)
	v_lshlrev_b32_e32 v132, 16, v228
	v_and_b32_e32 v133, 0xffff0000, v228
	v_lshlrev_b32_e32 v134, 16, v229
	v_and_b32_e32 v135, 0xffff0000, v229
	v_lshlrev_b32_e32 v136, 16, v230
	v_and_b32_e32 v137, 0xffff0000, v230
	v_lshlrev_b32_e32 v138, 16, v231
	v_and_b32_e32 v139, 0xffff0000, v231
	v_lshlrev_b32_e32 v244, 16, v232
	v_and_b32_e32 v245, 0xffff0000, v232
	v_lshlrev_b32_e32 v246, 16, v233
	v_and_b32_e32 v247, 0xffff0000, v233
	v_lshlrev_b32_e32 v248, 16, v234
	v_and_b32_e32 v249, 0xffff0000, v234
	v_lshlrev_b32_e32 v250, 16, v235
	v_and_b32_e32 v251, 0xffff0000, v235
	s_mov_b64 s[8:9], 0x5d8000
	v_lshl_add_u64 v[156:157], v[152:153], 0, s[8:9]
	global_load_dwordx4 v[228:231], v[156:157], off offset:-4096
	global_load_dwordx4 v[232:235], v[156:157], off offset:0
	v_max_f32_e32 v132, v132, v132
	v_max_f32_e32 v133, v133, v133
	v_max_f32_e32 v134, v134, v134
	v_max_f32_e32 v135, v135, v135
	v_max_f32_e32 v136, v136, v136
	v_max_f32_e32 v137, v137, v137
	v_max_f32_e32 v138, v138, v138
	v_max_f32_e32 v139, v139, v139
	v_med3_f32 v132, v132, s97, v226
	v_med3_f32 v133, v133, s97, v226
	v_med3_f32 v134, v134, s97, v226
	v_med3_f32 v135, v135, s97, v226
	v_med3_f32 v136, v136, s97, v226
	v_med3_f32 v137, v137, s97, v226
	v_med3_f32 v138, v138, s97, v226
	v_med3_f32 v139, v139, s97, v226
	v_mul_f32_e32 v132, 0xbfb8aa3b, v132
	v_mul_f32_e32 v133, 0xbfb8aa3b, v133
	v_mul_f32_e32 v134, 0xbfb8aa3b, v134
	v_mul_f32_e32 v135, 0xbfb8aa3b, v135
	v_mul_f32_e32 v136, 0xbfb8aa3b, v136
	v_mul_f32_e32 v137, 0xbfb8aa3b, v137
	v_mul_f32_e32 v138, 0xbfb8aa3b, v138
	v_mul_f32_e32 v139, 0xbfb8aa3b, v139
	v_exp_f32_e32 v132, v132
	v_exp_f32_e32 v133, v133
	v_exp_f32_e32 v134, v134
	v_exp_f32_e32 v135, v135
	v_exp_f32_e32 v136, v136
	v_exp_f32_e32 v137, v137
	v_exp_f32_e32 v138, v138
	v_exp_f32_e32 v139, v139
	v_add_f32_e32 v132, 1.0, v132
	v_add_f32_e32 v133, 1.0, v133
	v_add_f32_e32 v134, 1.0, v134
	v_add_f32_e32 v135, 1.0, v135
	v_add_f32_e32 v136, 1.0, v136
	v_add_f32_e32 v137, 1.0, v137
	v_add_f32_e32 v138, 1.0, v138
	v_add_f32_e32 v139, 1.0, v139
	v_rcp_f32_e32 v132, v132
	v_rcp_f32_e32 v133, v133
	v_rcp_f32_e32 v134, v134
	v_rcp_f32_e32 v135, v135
	v_rcp_f32_e32 v136, v136
	v_rcp_f32_e32 v137, v137
	v_rcp_f32_e32 v138, v138
	v_rcp_f32_e32 v139, v139
	v_max_f32_e32 v244, v244, v244
	v_max_f32_e32 v245, v245, v245
	v_max_f32_e32 v246, v246, v246
	v_max_f32_e32 v247, v247, v247
	v_max_f32_e32 v248, v248, v248
	v_max_f32_e32 v249, v249, v249
	v_max_f32_e32 v250, v250, v250
	v_max_f32_e32 v251, v251, v251
	v_med3_f32 v244, v244, s97, v226
	v_med3_f32 v245, v245, s97, v226
	v_med3_f32 v246, v246, s97, v226
	v_med3_f32 v247, v247, s97, v226
	v_med3_f32 v248, v248, s97, v226
	v_med3_f32 v249, v249, s97, v226
	v_med3_f32 v250, v250, s97, v226
	v_med3_f32 v251, v251, s97, v226
	v_mul_f32_e32 v244, 0xbfb8aa3b, v244
	v_mul_f32_e32 v245, 0xbfb8aa3b, v245
	v_mul_f32_e32 v246, 0xbfb8aa3b, v246
	v_mul_f32_e32 v247, 0xbfb8aa3b, v247
	v_mul_f32_e32 v248, 0xbfb8aa3b, v248
	v_mul_f32_e32 v249, 0xbfb8aa3b, v249
	v_mul_f32_e32 v250, 0xbfb8aa3b, v250
	v_mul_f32_e32 v251, 0xbfb8aa3b, v251
	v_exp_f32_e32 v244, v244
	v_exp_f32_e32 v245, v245
	v_exp_f32_e32 v246, v246
	v_exp_f32_e32 v247, v247
	v_exp_f32_e32 v248, v248
	v_exp_f32_e32 v249, v249
	v_exp_f32_e32 v250, v250
	v_exp_f32_e32 v251, v251
	v_add_f32_e32 v244, 1.0, v244
	v_add_f32_e32 v245, 1.0, v245
	v_add_f32_e32 v246, 1.0, v246
	v_add_f32_e32 v247, 1.0, v247
	v_add_f32_e32 v248, 1.0, v248
	v_add_f32_e32 v249, 1.0, v249
	v_add_f32_e32 v250, 1.0, v250
	v_add_f32_e32 v251, 1.0, v251
	v_pk_mul_f32 v[132:133], v[132:133], v[244:245]
	v_pk_mul_f32 v[134:135], v[134:135], v[246:247]
	v_pk_mul_f32 v[136:137], v[136:137], v[248:249]
	v_pk_mul_f32 v[138:139], v[138:139], v[250:251]
	v_pk_mul_f32 v[104:105], v[104:105], v[132:133]
	v_pk_mul_f32 v[106:107], v[106:107], v[134:135]
	v_pk_mul_f32 v[100:101], v[100:101], v[136:137]
	v_pk_mul_f32 v[102:103], v[102:103], v[138:139]
	s_waitcnt vmcnt(14)
;     static __device__ __forceinline__ float e1(float x) { return 1.0f + __expf(-fminf(fmaxf(x, -60.f), 60.f)); }
;     __device__ __forceinline__ void operator()(f32x4 (&acc)[2][2][4][2], const Unit& u, int wr, int wc, int fr, int fq) const {
;     ...
;                     const int col = col0 + bj * HALF;
;                     const bf16_t* gp = proj + (size_t)row * NP + C_GATE + u.z * D + col;
;                     const u32x4 ga = *(const u32x4*)gp;
;                     float sc[8];
;                     { float a[8]; unpack8(ga, a);
; #pragma unroll
;                       for (int j = 0; j < 8; ++j) sc[j] = __builtin_amdgcn_rcpf(e1(a[j])); }
;                     if (u.z < 2) { const u32x4 gb = *(const u32x4*)(gp + D); float b[8]; unpack8(gb, b);
; #pragma unroll
;                       for (int j = 0; j < 8; ++j) sc[j] *= e1(b[j]); }
;                     f32x4 v0 = acc[ai][bj][m][0], v1 = acc[ai][bj][m][1];
;                     v0[0] *= sc[0]; v0[1] *= sc[1]; v0[2] *= sc[2]; v0[3] *= sc[3]; v1[0] *= sc[4]; v1[1] *= sc[5]; v1[2] *= sc[6]; v1[3] *= sc[7];
;                     if (u.z < 2) { acc[ai][bj][m][0] = v0; acc[ai][bj][m][1] = v1; }
	v_lshlrev_b32_e32 v132, 16, v236
	v_and_b32_e32 v133, 0xffff0000, v236
	v_lshlrev_b32_e32 v134, 16, v237
	v_and_b32_e32 v135, 0xffff0000, v237
	v_lshlrev_b32_e32 v136, 16, v238
	v_and_b32_e32 v137, 0xffff0000, v238
	v_lshlrev_b32_e32 v138, 16, v239
	v_and_b32_e32 v139, 0xffff0000, v239
	v_lshlrev_b32_e32 v244, 16, v240
	v_and_b32_e32 v245, 0xffff0000, v240
	v_lshlrev_b32_e32 v246, 16, v241
	v_and_b32_e32 v247, 0xffff0000, v241
	v_lshlrev_b32_e32 v248, 16, v242
	v_and_b32_e32 v249, 0xffff0000, v242
	v_lshlrev_b32_e32 v250, 16, v243
	v_and_b32_e32 v251, 0xffff0000, v243
	s_mov_b64 s[8:9], 0x5d8000
	v_lshl_add_u64 v[156:157], v[152:153], 0, s[8:9]
	global_load_dwordx4 v[236:239], v[156:157], off offset:-3840
	global_load_dwordx4 v[240:243], v[156:157], off offset:256
	v_max_f32_e32 v132, v132, v132
	v_max_f32_e32 v133, v133, v133
	v_max_f32_e32 v134, v134, v134
	v_max_f32_e32 v135, v135, v135
	v_max_f32_e32 v136, v136, v136
	v_max_f32_e32 v137, v137, v137
	v_max_f32_e32 v138, v138, v138
	v_max_f32_e32 v139, v139, v139
	v_med3_f32 v132, v132, s97, v226
	v_med3_f32 v133, v133, s97, v226
	v_med3_f32 v134, v134, s97, v226
	v_med3_f32 v135, v135, s97, v226
	v_med3_f32 v136, v136, s97, v226
	v_med3_f32 v137, v137, s97, v226
	v_med3_f32 v138, v138, s97, v226
	v_med3_f32 v139, v139, s97, v226
	v_mul_f32_e32 v132, 0xbfb8aa3b, v132
	v_mul_f32_e32 v133, 0xbfb8aa3b, v133
	v_mul_f32_e32 v134, 0xbfb8aa3b, v134
	v_mul_f32_e32 v135, 0xbfb8aa3b, v135
	v_mul_f32_e32 v136, 0xbfb8aa3b, v136
	v_mul_f32_e32 v137, 0xbfb8aa3b, v137
	v_mul_f32_e32 v138, 0xbfb8aa3b, v138
	v_mul_f32_e32 v139, 0xbfb8aa3b, v139
	v_exp_f32_e32 v132, v132
	v_exp_f32_e32 v133, v133
	v_exp_f32_e32 v134, v134
	v_exp_f32_e32 v135, v135
	v_exp_f32_e32 v136, v136
	v_exp_f32_e32 v137, v137
	v_exp_f32_e32 v138, v138
	v_exp_f32_e32 v139, v139
	v_add_f32_e32 v132, 1.0, v132
	v_add_f32_e32 v133, 1.0, v133
	v_add_f32_e32 v134, 1.0, v134
	v_add_f32_e32 v135, 1.0, v135
	v_add_f32_e32 v136, 1.0, v136
	v_add_f32_e32 v137, 1.0, v137
	v_add_f32_e32 v138, 1.0, v138
	v_add_f32_e32 v139, 1.0, v139
	v_rcp_f32_e32 v132, v132
	v_rcp_f32_e32 v133, v133
	v_rcp_f32_e32 v134, v134
	v_rcp_f32_e32 v135, v135
	v_rcp_f32_e32 v136, v136
	v_rcp_f32_e32 v137, v137
	v_rcp_f32_e32 v138, v138
	v_rcp_f32_e32 v139, v139
	v_max_f32_e32 v244, v244, v244
	v_max_f32_e32 v245, v245, v245
	v_max_f32_e32 v246, v246, v246
	v_max_f32_e32 v247, v247, v247
	v_max_f32_e32 v248, v248, v248
	v_max_f32_e32 v249, v249, v249
	v_max_f32_e32 v250, v250, v250
	v_max_f32_e32 v251, v251, v251
	v_med3_f32 v244, v244, s97, v226
	v_med3_f32 v245, v245, s97, v226
	v_med3_f32 v246, v246, s97, v226
	v_med3_f32 v247, v247, s97, v226
	v_med3_f32 v248, v248, s97, v226
	v_med3_f32 v249, v249, s97, v226
	v_med3_f32 v250, v250, s97, v226
	v_med3_f32 v251, v251, s97, v226
	v_mul_f32_e32 v244, 0xbfb8aa3b, v244
	v_mul_f32_e32 v245, 0xbfb8aa3b, v245
	v_mul_f32_e32 v246, 0xbfb8aa3b, v246
	v_mul_f32_e32 v247, 0xbfb8aa3b, v247
	v_mul_f32_e32 v248, 0xbfb8aa3b, v248
	v_mul_f32_e32 v249, 0xbfb8aa3b, v249
	v_mul_f32_e32 v250, 0xbfb8aa3b, v250
	v_mul_f32_e32 v251, 0xbfb8aa3b, v251
	v_exp_f32_e32 v244, v244
	v_exp_f32_e32 v245, v245
	v_exp_f32_e32 v246, v246
	v_exp_f32_e32 v247, v247
	v_exp_f32_e32 v248, v248
	v_exp_f32_e32 v249, v249
	v_exp_f32_e32 v250, v250
	v_exp_f32_e32 v251, v251
	v_add_f32_e32 v244, 1.0, v244
	v_add_f32_e32 v245, 1.0, v245
	v_add_f32_e32 v246, 1.0, v246
	v_add_f32_e32 v247, 1.0, v247
	v_add_f32_e32 v248, 1.0, v248
	v_add_f32_e32 v249, 1.0, v249
	v_add_f32_e32 v250, 1.0, v250
	v_add_f32_e32 v251, 1.0, v251
	v_pk_mul_f32 v[132:133], v[132:133], v[244:245]
	v_pk_mul_f32 v[134:135], v[134:135], v[246:247]
	v_pk_mul_f32 v[136:137], v[136:137], v[248:249]
	v_pk_mul_f32 v[138:139], v[138:139], v[250:251]
	v_pk_mul_f32 v[72:73], v[72:73], v[132:133]
	v_pk_mul_f32 v[74:75], v[74:75], v[134:135]
	v_pk_mul_f32 v[68:69], v[68:69], v[136:137]
	v_pk_mul_f32 v[70:71], v[70:71], v[138:139]
	s_waitcnt vmcnt(14)
	v_lshlrev_b32_e32 v132, 16, v162
	v_and_b32_e32 v133, 0xffff0000, v162
	v_lshlrev_b32_e32 v134, 16, v163
	v_and_b32_e32 v135, 0xffff0000, v163
	v_lshlrev_b32_e32 v136, 16, v164
	v_and_b32_e32 v137, 0xffff0000, v164
	v_lshlrev_b32_e32 v138, 16, v165
	v_and_b32_e32 v139, 0xffff0000, v165
	v_lshlrev_b32_e32 v244, 16, v166
	v_and_b32_e32 v245, 0xffff0000, v166
	v_lshlrev_b32_e32 v246, 16, v167
	v_and_b32_e32 v247, 0xffff0000, v167
	v_lshlrev_b32_e32 v248, 16, v168
	v_and_b32_e32 v249, 0xffff0000, v168
	v_lshlrev_b32_e32 v250, 16, v169
	v_and_b32_e32 v251, 0xffff0000, v169
	v_max_f32_e32 v132, v132, v132
	v_max_f32_e32 v133, v133, v133
	v_max_f32_e32 v134, v134, v134
	v_max_f32_e32 v135, v135, v135
	v_max_f32_e32 v136, v136, v136
	v_max_f32_e32 v137, v137, v137
	v_max_f32_e32 v138, v138, v138
	v_max_f32_e32 v139, v139, v139
	v_med3_f32 v132, v132, s97, v226
	v_med3_f32 v133, v133, s97, v226
	v_med3_f32 v134, v134, s97, v226
	v_med3_f32 v135, v135, s97, v226
	v_med3_f32 v136, v136, s97, v226
	v_med3_f32 v137, v137, s97, v226
	v_med3_f32 v138, v138, s97, v226
	v_med3_f32 v139, v139, s97, v226
	v_mul_f32_e32 v132, 0xbfb8aa3b, v132
	v_mul_f32_e32 v133, 0xbfb8aa3b, v133
	v_mul_f32_e32 v134, 0xbfb8aa3b, v134
	v_mul_f32_e32 v135, 0xbfb8aa3b, v135
	v_mul_f32_e32 v136, 0xbfb8aa3b, v136
	v_mul_f32_e32 v137, 0xbfb8aa3b, v137
	v_mul_f32_e32 v138, 0xbfb8aa3b, v138
	v_mul_f32_e32 v139, 0xbfb8aa3b, v139
	v_exp_f32_e32 v132, v132
	v_exp_f32_e32 v133, v133
	v_exp_f32_e32 v134, v134
	v_exp_f32_e32 v135, v135
	v_exp_f32_e32 v136, v136
	v_exp_f32_e32 v137, v137
	v_exp_f32_e32 v138, v138
	v_exp_f32_e32 v139, v139
	v_add_f32_e32 v132, 1.0, v132
	v_add_f32_e32 v133, 1.0, v133
;     static __device__ __forceinline__ float e1(float x) { return 1.0f + __expf(-fminf(fmaxf(x, -60.f), 60.f)); }
;     __device__ __forceinline__ void operator()(f32x4 (&acc)[2][2][4][2], const Unit& u, int wr, int wc, int fr, int fq) const {
;     ...
;                     const int col = col0 + bj * HALF;
;                     const bf16_t* gp = proj + (size_t)row * NP + C_GATE + u.z * D + col;
;                     const u32x4 ga = *(const u32x4*)gp;
;                     float sc[8];
;                     { float a[8]; unpack8(ga, a);
; #pragma unroll
;                       for (int j = 0; j < 8; ++j) sc[j] = __builtin_amdgcn_rcpf(e1(a[j])); }
;                     if (u.z < 2) { const u32x4 gb = *(const u32x4*)(gp + D); float b[8]; unpack8(gb, b);
; #pragma unroll
;                       for (int j = 0; j < 8; ++j) sc[j] *= e1(b[j]); }
;                     f32x4 v0 = acc[ai][bj][m][0], v1 = acc[ai][bj][m][1];
;                     v0[0] *= sc[0]; v0[1] *= sc[1]; v0[2] *= sc[2]; v0[3] *= sc[3]; v1[0] *= sc[4]; v1[1] *= sc[5]; v1[2] *= sc[6]; v1[3] *= sc[7];
;                     if (u.z < 2) { acc[ai][bj][m][0] = v0; acc[ai][bj][m][1] = v1; }
	v_add_f32_e32 v134, 1.0, v134
	v_add_f32_e32 v135, 1.0, v135
	v_add_f32_e32 v136, 1.0, v136
	v_add_f32_e32 v137, 1.0, v137
	v_add_f32_e32 v138, 1.0, v138
	v_add_f32_e32 v139, 1.0, v139
	v_rcp_f32_e32 v132, v132
	v_rcp_f32_e32 v133, v133
	v_rcp_f32_e32 v134, v134
	v_rcp_f32_e32 v135, v135
	v_rcp_f32_e32 v136, v136
	v_rcp_f32_e32 v137, v137
	v_rcp_f32_e32 v138, v138
	v_rcp_f32_e32 v139, v139
	v_max_f32_e32 v244, v244, v244
	v_max_f32_e32 v245, v245, v245
	v_max_f32_e32 v246, v246, v246
	v_max_f32_e32 v247, v247, v247
	v_max_f32_e32 v248, v248, v248
	v_max_f32_e32 v249, v249, v249
	v_max_f32_e32 v250, v250, v250
	v_max_f32_e32 v251, v251, v251
	v_med3_f32 v244, v244, s97, v226
	v_med3_f32 v245, v245, s97, v226
	v_med3_f32 v246, v246, s97, v226
	v_med3_f32 v247, v247, s97, v226
	v_med3_f32 v248, v248, s97, v226
	v_med3_f32 v249, v249, s97, v226
	v_med3_f32 v250, v250, s97, v226
	v_med3_f32 v251, v251, s97, v226
	v_mul_f32_e32 v244, 0xbfb8aa3b, v244
	v_mul_f32_e32 v245, 0xbfb8aa3b, v245
	v_mul_f32_e32 v246, 0xbfb8aa3b, v246
	v_mul_f32_e32 v247, 0xbfb8aa3b, v247
	v_mul_f32_e32 v248, 0xbfb8aa3b, v248
	v_mul_f32_e32 v249, 0xbfb8aa3b, v249
	v_mul_f32_e32 v250, 0xbfb8aa3b, v250
	v_mul_f32_e32 v251, 0xbfb8aa3b, v251
	v_exp_f32_e32 v244, v244
	v_exp_f32_e32 v245, v245
	v_exp_f32_e32 v246, v246
	v_exp_f32_e32 v247, v247
	v_exp_f32_e32 v248, v248
	v_exp_f32_e32 v249, v249
	v_exp_f32_e32 v250, v250
	v_exp_f32_e32 v251, v251
	v_add_f32_e32 v244, 1.0, v244
	v_add_f32_e32 v245, 1.0, v245
	v_add_f32_e32 v246, 1.0, v246
	v_add_f32_e32 v247, 1.0, v247
	v_add_f32_e32 v248, 1.0, v248
	v_add_f32_e32 v249, 1.0, v249
	v_add_f32_e32 v250, 1.0, v250
	v_add_f32_e32 v251, 1.0, v251
	v_pk_mul_f32 v[132:133], v[132:133], v[244:245]
	v_pk_mul_f32 v[134:135], v[134:135], v[246:247]
	v_pk_mul_f32 v[136:137], v[136:137], v[248:249]
	v_pk_mul_f32 v[138:139], v[138:139], v[250:251]
	v_pk_mul_f32 v[64:65], v[64:65], v[132:133]
	v_pk_mul_f32 v[66:67], v[66:67], v[134:135]
	v_pk_mul_f32 v[60:61], v[60:61], v[136:137]
	v_pk_mul_f32 v[62:63], v[62:63], v[138:139]
	s_waitcnt vmcnt(12)
	v_lshlrev_b32_e32 v132, 16, v170
	v_and_b32_e32 v133, 0xffff0000, v170
	v_lshlrev_b32_e32 v134, 16, v171
	v_and_b32_e32 v135, 0xffff0000, v171
	v_lshlrev_b32_e32 v136, 16, v172
	v_and_b32_e32 v137, 0xffff0000, v172
	v_lshlrev_b32_e32 v138, 16, v173
	v_and_b32_e32 v139, 0xffff0000, v173
	v_lshlrev_b32_e32 v244, 16, v174
	v_and_b32_e32 v245, 0xffff0000, v174
	v_lshlrev_b32_e32 v246, 16, v175
	v_and_b32_e32 v247, 0xffff0000, v175
	v_lshlrev_b32_e32 v248, 16, v176
	v_and_b32_e32 v249, 0xffff0000, v176
	v_lshlrev_b32_e32 v250, 16, v177
	v_and_b32_e32 v251, 0xffff0000, v177
	v_max_f32_e32 v132, v132, v132
	v_max_f32_e32 v133, v133, v133
	v_max_f32_e32 v134, v134, v134
	v_max_f32_e32 v135, v135, v135
	v_max_f32_e32 v136, v136, v136
	v_max_f32_e32 v137, v137, v137
	v_max_f32_e32 v138, v138, v138
	v_max_f32_e32 v139, v139, v139
	v_med3_f32 v132, v132, s97, v226
	v_med3_f32 v133, v133, s97, v226
	v_med3_f32 v134, v134, s97, v226
	v_med3_f32 v135, v135, s97, v226
	v_med3_f32 v136, v136, s97, v226
	v_med3_f32 v137, v137, s97, v226
	v_med3_f32 v138, v138, s97, v226
	v_med3_f32 v139, v139, s97, v226
	v_mul_f32_e32 v132, 0xbfb8aa3b, v132
	v_mul_f32_e32 v133, 0xbfb8aa3b, v133
	v_mul_f32_e32 v134, 0xbfb8aa3b, v134
	v_mul_f32_e32 v135, 0xbfb8aa3b, v135
	v_mul_f32_e32 v136, 0xbfb8aa3b, v136
	v_mul_f32_e32 v137, 0xbfb8aa3b, v137
	v_mul_f32_e32 v138, 0xbfb8aa3b, v138
	v_mul_f32_e32 v139, 0xbfb8aa3b, v139
	v_exp_f32_e32 v132, v132
	v_exp_f32_e32 v133, v133
	v_exp_f32_e32 v134, v134
	v_exp_f32_e32 v135, v135
	v_exp_f32_e32 v136, v136
	v_exp_f32_e32 v137, v137
	v_exp_f32_e32 v138, v138
	v_exp_f32_e32 v139, v139
	v_add_f32_e32 v132, 1.0, v132
	v_add_f32_e32 v133, 1.0, v133
	v_add_f32_e32 v134, 1.0, v134
	v_add_f32_e32 v135, 1.0, v135
	v_add_f32_e32 v136, 1.0, v136
	v_add_f32_e32 v137, 1.0, v137
	v_add_f32_e32 v138, 1.0, v138
	v_add_f32_e32 v139, 1.0, v139
	v_rcp_f32_e32 v132, v132
	v_rcp_f32_e32 v133, v133
	v_rcp_f32_e32 v134, v134
	v_rcp_f32_e32 v135, v135
	v_rcp_f32_e32 v136, v136
	v_rcp_f32_e32 v137, v137
	v_rcp_f32_e32 v138, v138
	v_rcp_f32_e32 v139, v139
	v_max_f32_e32 v244, v244, v244
	v_max_f32_e32 v245, v245, v245
	v_max_f32_e32 v246, v246, v246
	v_max_f32_e32 v247, v247, v247
	v_max_f32_e32 v248, v248, v248
	v_max_f32_e32 v249, v249, v249
	v_max_f32_e32 v250, v250, v250
	v_max_f32_e32 v251, v251, v251
	v_med3_f32 v244, v244, s97, v226
	v_med3_f32 v245, v245, s97, v226
	v_med3_f32 v246, v246, s97, v226
	v_med3_f32 v247, v247, s97, v226
	v_med3_f32 v248, v248, s97, v226
	v_med3_f32 v249, v249, s97, v226
	v_med3_f32 v250, v250, s97, v226
	v_med3_f32 v251, v251, s97, v226
	v_mul_f32_e32 v244, 0xbfb8aa3b, v244
	v_mul_f32_e32 v245, 0xbfb8aa3b, v245
	v_mul_f32_e32 v246, 0xbfb8aa3b, v246
	v_mul_f32_e32 v247, 0xbfb8aa3b, v247
	v_mul_f32_e32 v248, 0xbfb8aa3b, v248
	v_mul_f32_e32 v249, 0xbfb8aa3b, v249
	v_mul_f32_e32 v250, 0xbfb8aa3b, v250
	v_mul_f32_e32 v251, 0xbfb8aa3b, v251
	v_exp_f32_e32 v244, v244
	v_exp_f32_e32 v245, v245
	v_exp_f32_e32 v246, v246
	v_exp_f32_e32 v247, v247
	v_exp_f32_e32 v248, v248
	v_exp_f32_e32 v249, v249
	v_exp_f32_e32 v250, v250
	v_exp_f32_e32 v251, v251
	v_add_f32_e32 v244, 1.0, v244
	v_add_f32_e32 v245, 1.0, v245
	v_add_f32_e32 v246, 1.0, v246
	v_add_f32_e32 v247, 1.0, v247
	v_add_f32_e32 v248, 1.0, v248
	v_add_f32_e32 v249, 1.0, v249
	v_add_f32_e32 v250, 1.0, v250
	v_add_f32_e32 v251, 1.0, v251
	v_pk_mul_f32 v[132:133], v[132:133], v[244:245]
	v_pk_mul_f32 v[134:135], v[134:135], v[246:247]
	v_pk_mul_f32 v[136:137], v[136:137], v[248:249]
	v_pk_mul_f32 v[138:139], v[138:139], v[250:251]
	v_pk_mul_f32 v[32:33], v[32:33], v[132:133]
	v_pk_mul_f32 v[34:35], v[34:35], v[134:135]
	v_pk_mul_f32 v[28:29], v[28:29], v[136:137]
	v_pk_mul_f32 v[30:31], v[30:31], v[138:139]
	s_waitcnt vmcnt(10)
;     static __device__ __forceinline__ float e1(float x) { return 1.0f + __expf(-fminf(fmaxf(x, -60.f), 60.f)); }
;     __device__ __forceinline__ void operator()(f32x4 (&acc)[2][2][4][2], const Unit& u, int wr, int wc, int fr, int fq) const {
;     ...
;                     const int col = col0 + bj * HALF;
;                     const bf16_t* gp = proj + (size_t)row * NP + C_GATE + u.z * D + col;
;                     const u32x4 ga = *(const u32x4*)gp;
;                     float sc[8];
;                     { float a[8]; unpack8(ga, a);
; #pragma unroll
;                       for (int j = 0; j < 8; ++j) sc[j] = __builtin_amdgcn_rcpf(e1(a[j])); }
;                     if (u.z < 2) { const u32x4 gb = *(const u32x4*)(gp + D); float b[8]; unpack8(gb, b);
; #pragma unroll
;                       for (int j = 0; j < 8; ++j) sc[j] *= e1(b[j]); }
;                     f32x4 v0 = acc[ai][bj][m][0], v1 = acc[ai][bj][m][1];
;                     v0[0] *= sc[0]; v0[1] *= sc[1]; v0[2] *= sc[2]; v0[3] *= sc[3]; v1[0] *= sc[4]; v1[1] *= sc[5]; v1[2] *= sc[6]; v1[3] *= sc[7];
;                     if (u.z < 2) { acc[ai][bj][m][0] = v0; acc[ai][bj][m][1] = v1; }
	v_lshlrev_b32_e32 v132, 16, v178
	v_and_b32_e32 v133, 0xffff0000, v178
	v_lshlrev_b32_e32 v134, 16, v179
	v_and_b32_e32 v135, 0xffff0000, v179
	v_lshlrev_b32_e32 v136, 16, v180
	v_and_b32_e32 v137, 0xffff0000, v180
	v_lshlrev_b32_e32 v138, 16, v181
	v_and_b32_e32 v139, 0xffff0000, v181
	v_lshlrev_b32_e32 v244, 16, v182
	v_and_b32_e32 v245, 0xffff0000, v182
	v_lshlrev_b32_e32 v246, 16, v183
	v_and_b32_e32 v247, 0xffff0000, v183
	v_lshlrev_b32_e32 v248, 16, v184
	v_and_b32_e32 v249, 0xffff0000, v184
	v_lshlrev_b32_e32 v250, 16, v185
	v_and_b32_e32 v251, 0xffff0000, v185
	v_max_f32_e32 v132, v132, v132
	v_max_f32_e32 v133, v133, v133
	v_max_f32_e32 v134, v134, v134
	v_max_f32_e32 v135, v135, v135
	v_max_f32_e32 v136, v136, v136
	v_max_f32_e32 v137, v137, v137
	v_max_f32_e32 v138, v138, v138
	v_max_f32_e32 v139, v139, v139
	v_med3_f32 v132, v132, s97, v226
	v_med3_f32 v133, v133, s97, v226
	v_med3_f32 v134, v134, s97, v226
	v_med3_f32 v135, v135, s97, v226
	v_med3_f32 v136, v136, s97, v226
	v_med3_f32 v137, v137, s97, v226
	v_med3_f32 v138, v138, s97, v226
	v_med3_f32 v139, v139, s97, v226
	v_mul_f32_e32 v132, 0xbfb8aa3b, v132
	v_mul_f32_e32 v133, 0xbfb8aa3b, v133
	v_mul_f32_e32 v134, 0xbfb8aa3b, v134
	v_mul_f32_e32 v135, 0xbfb8aa3b, v135
	v_mul_f32_e32 v136, 0xbfb8aa3b, v136
	v_mul_f32_e32 v137, 0xbfb8aa3b, v137
	v_mul_f32_e32 v138, 0xbfb8aa3b, v138
	v_mul_f32_e32 v139, 0xbfb8aa3b, v139
	v_exp_f32_e32 v132, v132
	v_exp_f32_e32 v133, v133
	v_exp_f32_e32 v134, v134
	v_exp_f32_e32 v135, v135
	v_exp_f32_e32 v136, v136
	v_exp_f32_e32 v137, v137
	v_exp_f32_e32 v138, v138
	v_exp_f32_e32 v139, v139
	v_add_f32_e32 v132, 1.0, v132
	v_add_f32_e32 v133, 1.0, v133
	v_add_f32_e32 v134, 1.0, v134
	v_add_f32_e32 v135, 1.0, v135
	v_add_f32_e32 v136, 1.0, v136
	v_add_f32_e32 v137, 1.0, v137
	v_add_f32_e32 v138, 1.0, v138
	v_add_f32_e32 v139, 1.0, v139
	v_rcp_f32_e32 v132, v132
	v_rcp_f32_e32 v133, v133
	v_rcp_f32_e32 v134, v134
	v_rcp_f32_e32 v135, v135
	v_rcp_f32_e32 v136, v136
	v_rcp_f32_e32 v137, v137
	v_rcp_f32_e32 v138, v138
	v_rcp_f32_e32 v139, v139
	v_max_f32_e32 v244, v244, v244
	v_max_f32_e32 v245, v245, v245
	v_max_f32_e32 v246, v246, v246
	v_max_f32_e32 v247, v247, v247
	v_max_f32_e32 v248, v248, v248
	v_max_f32_e32 v249, v249, v249
	v_max_f32_e32 v250, v250, v250
	v_max_f32_e32 v251, v251, v251
	v_med3_f32 v244, v244, s97, v226
	v_med3_f32 v245, v245, s97, v226
	v_med3_f32 v246, v246, s97, v226
	v_med3_f32 v247, v247, s97, v226
	v_med3_f32 v248, v248, s97, v226
	v_med3_f32 v249, v249, s97, v226
	v_med3_f32 v250, v250, s97, v226
	v_med3_f32 v251, v251, s97, v226
	v_mul_f32_e32 v244, 0xbfb8aa3b, v244
	v_mul_f32_e32 v245, 0xbfb8aa3b, v245
	v_mul_f32_e32 v246, 0xbfb8aa3b, v246
	v_mul_f32_e32 v247, 0xbfb8aa3b, v247
	v_mul_f32_e32 v248, 0xbfb8aa3b, v248
	v_mul_f32_e32 v249, 0xbfb8aa3b, v249
	v_mul_f32_e32 v250, 0xbfb8aa3b, v250
	v_mul_f32_e32 v251, 0xbfb8aa3b, v251
	v_exp_f32_e32 v244, v244
	v_exp_f32_e32 v245, v245
	v_exp_f32_e32 v246, v246
	v_exp_f32_e32 v247, v247
	v_exp_f32_e32 v248, v248
	v_exp_f32_e32 v249, v249
	v_exp_f32_e32 v250, v250
	v_exp_f32_e32 v251, v251
	v_add_f32_e32 v244, 1.0, v244
	v_add_f32_e32 v245, 1.0, v245
	v_add_f32_e32 v246, 1.0, v246
	v_add_f32_e32 v247, 1.0, v247
	v_add_f32_e32 v248, 1.0, v248
	v_add_f32_e32 v249, 1.0, v249
	v_add_f32_e32 v250, 1.0, v250
	v_add_f32_e32 v251, 1.0, v251
	v_pk_mul_f32 v[132:133], v[132:133], v[244:245]
	v_pk_mul_f32 v[134:135], v[134:135], v[246:247]
	v_pk_mul_f32 v[136:137], v[136:137], v[248:249]
	v_pk_mul_f32 v[138:139], v[138:139], v[250:251]
	v_pk_mul_f32 v[56:57], v[56:57], v[132:133]
	v_pk_mul_f32 v[58:59], v[58:59], v[134:135]
	v_pk_mul_f32 v[52:53], v[52:53], v[136:137]
	v_pk_mul_f32 v[54:55], v[54:55], v[138:139]
	s_waitcnt vmcnt(8)
	v_lshlrev_b32_e32 v132, 16, v186
	v_and_b32_e32 v133, 0xffff0000, v186
	v_lshlrev_b32_e32 v134, 16, v187
	v_and_b32_e32 v135, 0xffff0000, v187
	v_lshlrev_b32_e32 v136, 16, v188
	v_and_b32_e32 v137, 0xffff0000, v188
	v_lshlrev_b32_e32 v138, 16, v189
	v_and_b32_e32 v139, 0xffff0000, v189
	v_lshlrev_b32_e32 v244, 16, v190
	v_and_b32_e32 v245, 0xffff0000, v190
	v_lshlrev_b32_e32 v246, 16, v191
	v_and_b32_e32 v247, 0xffff0000, v191
	v_lshlrev_b32_e32 v248, 16, v192
	v_and_b32_e32 v249, 0xffff0000, v192
	v_lshlrev_b32_e32 v250, 16, v193
	v_and_b32_e32 v251, 0xffff0000, v193
	v_max_f32_e32 v132, v132, v132
	v_max_f32_e32 v133, v133, v133
	v_max_f32_e32 v134, v134, v134
	v_max_f32_e32 v135, v135, v135
	v_max_f32_e32 v136, v136, v136
	v_max_f32_e32 v137, v137, v137
	v_max_f32_e32 v138, v138, v138
	v_max_f32_e32 v139, v139, v139
	v_med3_f32 v132, v132, s97, v226
	v_med3_f32 v133, v133, s97, v226
	v_med3_f32 v134, v134, s97, v226
	v_med3_f32 v135, v135, s97, v226
	v_med3_f32 v136, v136, s97, v226
	v_med3_f32 v137, v137, s97, v226
	v_med3_f32 v138, v138, s97, v226
	v_med3_f32 v139, v139, s97, v226
	v_mul_f32_e32 v132, 0xbfb8aa3b, v132
	v_mul_f32_e32 v133, 0xbfb8aa3b, v133
	v_mul_f32_e32 v134, 0xbfb8aa3b, v134
	v_mul_f32_e32 v135, 0xbfb8aa3b, v135
	v_mul_f32_e32 v136, 0xbfb8aa3b, v136
	v_mul_f32_e32 v137, 0xbfb8aa3b, v137
	v_mul_f32_e32 v138, 0xbfb8aa3b, v138
	v_mul_f32_e32 v139, 0xbfb8aa3b, v139
	v_exp_f32_e32 v132, v132
	v_exp_f32_e32 v133, v133
	v_exp_f32_e32 v134, v134
	v_exp_f32_e32 v135, v135
	v_exp_f32_e32 v136, v136
	v_exp_f32_e32 v137, v137
	v_exp_f32_e32 v138, v138
	v_exp_f32_e32 v139, v139
	v_add_f32_e32 v132, 1.0, v132
	v_add_f32_e32 v133, 1.0, v133
	v_add_f32_e32 v134, 1.0, v134
	v_add_f32_e32 v135, 1.0, v135
	v_add_f32_e32 v136, 1.0, v136
	v_add_f32_e32 v137, 1.0, v137
	v_add_f32_e32 v138, 1.0, v138
	v_add_f32_e32 v139, 1.0, v139
	v_rcp_f32_e32 v132, v132
;     static __device__ __forceinline__ float e1(float x) { return 1.0f + __expf(-fminf(fmaxf(x, -60.f), 60.f)); }
;     __device__ __forceinline__ void operator()(f32x4 (&acc)[2][2][4][2], const Unit& u, int wr, int wc, int fr, int fq) const {
;     ...
;                     const int col = col0 + bj * HALF;
;                     const bf16_t* gp = proj + (size_t)row * NP + C_GATE + u.z * D + col;
;                     const u32x4 ga = *(const u32x4*)gp;
;                     float sc[8];
;                     { float a[8]; unpack8(ga, a);
; #pragma unroll
;                       for (int j = 0; j < 8; ++j) sc[j] = __builtin_amdgcn_rcpf(e1(a[j])); }
;                     if (u.z < 2) { const u32x4 gb = *(const u32x4*)(gp + D); float b[8]; unpack8(gb, b);
; #pragma unroll
;                       for (int j = 0; j < 8; ++j) sc[j] *= e1(b[j]); }
;                     f32x4 v0 = acc[ai][bj][m][0], v1 = acc[ai][bj][m][1];
;                     v0[0] *= sc[0]; v0[1] *= sc[1]; v0[2] *= sc[2]; v0[3] *= sc[3]; v1[0] *= sc[4]; v1[1] *= sc[5]; v1[2] *= sc[6]; v1[3] *= sc[7];
;                     if (u.z < 2) { acc[ai][bj][m][0] = v0; acc[ai][bj][m][1] = v1; }
	v_rcp_f32_e32 v133, v133
	v_rcp_f32_e32 v134, v134
	v_rcp_f32_e32 v135, v135
	v_rcp_f32_e32 v136, v136
	v_rcp_f32_e32 v137, v137
	v_rcp_f32_e32 v138, v138
	v_rcp_f32_e32 v139, v139
	v_max_f32_e32 v244, v244, v244
	v_max_f32_e32 v245, v245, v245
	v_max_f32_e32 v246, v246, v246
	v_max_f32_e32 v247, v247, v247
	v_max_f32_e32 v248, v248, v248
	v_max_f32_e32 v249, v249, v249
	v_max_f32_e32 v250, v250, v250
	v_max_f32_e32 v251, v251, v251
	v_med3_f32 v244, v244, s97, v226
	v_med3_f32 v245, v245, s97, v226
	v_med3_f32 v246, v246, s97, v226
	v_med3_f32 v247, v247, s97, v226
	v_med3_f32 v248, v248, s97, v226
	v_med3_f32 v249, v249, s97, v226
	v_med3_f32 v250, v250, s97, v226
	v_med3_f32 v251, v251, s97, v226
	v_mul_f32_e32 v244, 0xbfb8aa3b, v244
	v_mul_f32_e32 v245, 0xbfb8aa3b, v245
	v_mul_f32_e32 v246, 0xbfb8aa3b, v246
	v_mul_f32_e32 v247, 0xbfb8aa3b, v247
	v_mul_f32_e32 v248, 0xbfb8aa3b, v248
	v_mul_f32_e32 v249, 0xbfb8aa3b, v249
	v_mul_f32_e32 v250, 0xbfb8aa3b, v250
	v_mul_f32_e32 v251, 0xbfb8aa3b, v251
	v_exp_f32_e32 v244, v244
	v_exp_f32_e32 v245, v245
	v_exp_f32_e32 v246, v246
	v_exp_f32_e32 v247, v247
	v_exp_f32_e32 v248, v248
	v_exp_f32_e32 v249, v249
	v_exp_f32_e32 v250, v250
	v_exp_f32_e32 v251, v251
	v_add_f32_e32 v244, 1.0, v244
	v_add_f32_e32 v245, 1.0, v245
	v_add_f32_e32 v246, 1.0, v246
	v_add_f32_e32 v247, 1.0, v247
	v_add_f32_e32 v248, 1.0, v248
	v_add_f32_e32 v249, 1.0, v249
	v_add_f32_e32 v250, 1.0, v250
	v_add_f32_e32 v251, 1.0, v251
	v_pk_mul_f32 v[132:133], v[132:133], v[244:245]
	v_pk_mul_f32 v[134:135], v[134:135], v[246:247]
	v_pk_mul_f32 v[136:137], v[136:137], v[248:249]
	v_pk_mul_f32 v[138:139], v[138:139], v[250:251]
	v_pk_mul_f32 v[24:25], v[24:25], v[132:133]
	v_pk_mul_f32 v[26:27], v[26:27], v[134:135]
	v_pk_mul_f32 v[20:21], v[20:21], v[136:137]
	v_pk_mul_f32 v[22:23], v[22:23], v[138:139]
	s_waitcnt vmcnt(6)
	v_lshlrev_b32_e32 v132, 16, v194
	v_and_b32_e32 v133, 0xffff0000, v194
	v_lshlrev_b32_e32 v134, 16, v195
	v_and_b32_e32 v135, 0xffff0000, v195
	v_lshlrev_b32_e32 v136, 16, v196
	v_and_b32_e32 v137, 0xffff0000, v196
	v_lshlrev_b32_e32 v138, 16, v197
	v_and_b32_e32 v139, 0xffff0000, v197
	v_lshlrev_b32_e32 v244, 16, v198
	v_and_b32_e32 v245, 0xffff0000, v198
	v_lshlrev_b32_e32 v246, 16, v199
	v_and_b32_e32 v247, 0xffff0000, v199
	v_lshlrev_b32_e32 v248, 16, v200
	v_and_b32_e32 v249, 0xffff0000, v200
	v_lshlrev_b32_e32 v250, 16, v201
	v_and_b32_e32 v251, 0xffff0000, v201
	v_max_f32_e32 v132, v132, v132
	v_max_f32_e32 v133, v133, v133
	v_max_f32_e32 v134, v134, v134
	v_max_f32_e32 v135, v135, v135
	v_max_f32_e32 v136, v136, v136
	v_max_f32_e32 v137, v137, v137
	v_max_f32_e32 v138, v138, v138
	v_max_f32_e32 v139, v139, v139
	v_med3_f32 v132, v132, s97, v226
	v_med3_f32 v133, v133, s97, v226
	v_med3_f32 v134, v134, s97, v226
	v_med3_f32 v135, v135, s97, v226
	v_med3_f32 v136, v136, s97, v226
	v_med3_f32 v137, v137, s97, v226
	v_med3_f32 v138, v138, s97, v226
	v_med3_f32 v139, v139, s97, v226
	v_mul_f32_e32 v132, 0xbfb8aa3b, v132
	v_mul_f32_e32 v133, 0xbfb8aa3b, v133
	v_mul_f32_e32 v134, 0xbfb8aa3b, v134
	v_mul_f32_e32 v135, 0xbfb8aa3b, v135
	v_mul_f32_e32 v136, 0xbfb8aa3b, v136
	v_mul_f32_e32 v137, 0xbfb8aa3b, v137
	v_mul_f32_e32 v138, 0xbfb8aa3b, v138
	v_mul_f32_e32 v139, 0xbfb8aa3b, v139
	v_exp_f32_e32 v132, v132
	v_exp_f32_e32 v133, v133
	v_exp_f32_e32 v134, v134
	v_exp_f32_e32 v135, v135
	v_exp_f32_e32 v136, v136
	v_exp_f32_e32 v137, v137
	v_exp_f32_e32 v138, v138
	v_exp_f32_e32 v139, v139
	v_add_f32_e32 v132, 1.0, v132
	v_add_f32_e32 v133, 1.0, v133
	v_add_f32_e32 v134, 1.0, v134
	v_add_f32_e32 v135, 1.0, v135
	v_add_f32_e32 v136, 1.0, v136
	v_add_f32_e32 v137, 1.0, v137
	v_add_f32_e32 v138, 1.0, v138
	v_add_f32_e32 v139, 1.0, v139
	v_rcp_f32_e32 v132, v132
	v_rcp_f32_e32 v133, v133
	v_rcp_f32_e32 v134, v134
	v_rcp_f32_e32 v135, v135
	v_rcp_f32_e32 v136, v136
	v_rcp_f32_e32 v137, v137
	v_rcp_f32_e32 v138, v138
	v_rcp_f32_e32 v139, v139
	v_max_f32_e32 v244, v244, v244
	v_max_f32_e32 v245, v245, v245
	v_max_f32_e32 v246, v246, v246
	v_max_f32_e32 v247, v247, v247
	v_max_f32_e32 v248, v248, v248
	v_max_f32_e32 v249, v249, v249
	v_max_f32_e32 v250, v250, v250
	v_max_f32_e32 v251, v251, v251
	v_med3_f32 v244, v244, s97, v226
	v_med3_f32 v245, v245, s97, v226
	v_med3_f32 v246, v246, s97, v226
	v_med3_f32 v247, v247, s97, v226
	v_med3_f32 v248, v248, s97, v226
	v_med3_f32 v249, v249, s97, v226
	v_med3_f32 v250, v250, s97, v226
	v_med3_f32 v251, v251, s97, v226
	v_mul_f32_e32 v244, 0xbfb8aa3b, v244
	v_mul_f32_e32 v245, 0xbfb8aa3b, v245
	v_mul_f32_e32 v246, 0xbfb8aa3b, v246
	v_mul_f32_e32 v247, 0xbfb8aa3b, v247
	v_mul_f32_e32 v248, 0xbfb8aa3b, v248
	v_mul_f32_e32 v249, 0xbfb8aa3b, v249
	v_mul_f32_e32 v250, 0xbfb8aa3b, v250
	v_mul_f32_e32 v251, 0xbfb8aa3b, v251
	v_exp_f32_e32 v244, v244
	v_exp_f32_e32 v245, v245
	v_exp_f32_e32 v246, v246
	v_exp_f32_e32 v247, v247
	v_exp_f32_e32 v248, v248
	v_exp_f32_e32 v249, v249
	v_exp_f32_e32 v250, v250
	v_exp_f32_e32 v251, v251
	v_add_f32_e32 v244, 1.0, v244
	v_add_f32_e32 v245, 1.0, v245
	v_add_f32_e32 v246, 1.0, v246
	v_add_f32_e32 v247, 1.0, v247
	v_add_f32_e32 v248, 1.0, v248
	v_add_f32_e32 v249, 1.0, v249
	v_add_f32_e32 v250, 1.0, v250
	v_add_f32_e32 v251, 1.0, v251
	v_pk_mul_f32 v[132:133], v[132:133], v[244:245]
	v_pk_mul_f32 v[134:135], v[134:135], v[246:247]
	v_pk_mul_f32 v[136:137], v[136:137], v[248:249]
	v_pk_mul_f32 v[138:139], v[138:139], v[250:251]
	v_pk_mul_f32 v[48:49], v[48:49], v[132:133]
	v_pk_mul_f32 v[50:51], v[50:51], v[134:135]
	v_pk_mul_f32 v[44:45], v[44:45], v[136:137]
	v_pk_mul_f32 v[46:47], v[46:47], v[138:139]
	s_waitcnt vmcnt(4)
;     static __device__ __forceinline__ float e1(float x) { return 1.0f + __expf(-fminf(fmaxf(x, -60.f), 60.f)); }
;     __device__ __forceinline__ void operator()(f32x4 (&acc)[2][2][4][2], const Unit& u, int wr, int wc, int fr, int fq) const {
;     ...
;                     const int col = col0 + bj * HALF;
;                     const bf16_t* gp = proj + (size_t)row * NP + C_GATE + u.z * D + col;
;                     const u32x4 ga = *(const u32x4*)gp;
;                     float sc[8];
;                     { float a[8]; unpack8(ga, a);
; #pragma unroll
;                       for (int j = 0; j < 8; ++j) sc[j] = __builtin_amdgcn_rcpf(e1(a[j])); }
;                     if (u.z < 2) { const u32x4 gb = *(const u32x4*)(gp + D); float b[8]; unpack8(gb, b);
; #pragma unroll
;                       for (int j = 0; j < 8; ++j) sc[j] *= e1(b[j]); }
;                     f32x4 v0 = acc[ai][bj][m][0], v1 = acc[ai][bj][m][1];
;                     v0[0] *= sc[0]; v0[1] *= sc[1]; v0[2] *= sc[2]; v0[3] *= sc[3]; v1[0] *= sc[4]; v1[1] *= sc[5]; v1[2] *= sc[6]; v1[3] *= sc[7];
;                     if (u.z < 2) { acc[ai][bj][m][0] = v0; acc[ai][bj][m][1] = v1; }
	v_lshlrev_b32_e32 v132, 16, v206
	v_and_b32_e32 v133, 0xffff0000, v206
	v_lshlrev_b32_e32 v134, 16, v207
	v_and_b32_e32 v135, 0xffff0000, v207
	v_lshlrev_b32_e32 v136, 16, v208
	v_and_b32_e32 v137, 0xffff0000, v208
	v_lshlrev_b32_e32 v138, 16, v209
	v_and_b32_e32 v139, 0xffff0000, v209
	v_lshlrev_b32_e32 v244, 16, v210
	v_and_b32_e32 v245, 0xffff0000, v210
	v_lshlrev_b32_e32 v246, 16, v211
	v_and_b32_e32 v247, 0xffff0000, v211
	v_lshlrev_b32_e32 v248, 16, v212
	v_and_b32_e32 v249, 0xffff0000, v212
	v_lshlrev_b32_e32 v250, 16, v213
	v_and_b32_e32 v251, 0xffff0000, v213
	v_max_f32_e32 v132, v132, v132
	v_max_f32_e32 v133, v133, v133
	v_max_f32_e32 v134, v134, v134
	v_max_f32_e32 v135, v135, v135
	v_max_f32_e32 v136, v136, v136
	v_max_f32_e32 v137, v137, v137
	v_max_f32_e32 v138, v138, v138
	v_max_f32_e32 v139, v139, v139
	v_med3_f32 v132, v132, s97, v226
	v_med3_f32 v133, v133, s97, v226
	v_med3_f32 v134, v134, s97, v226
	v_med3_f32 v135, v135, s97, v226
	v_med3_f32 v136, v136, s97, v226
	v_med3_f32 v137, v137, s97, v226
	v_med3_f32 v138, v138, s97, v226
	v_med3_f32 v139, v139, s97, v226
	v_mul_f32_e32 v132, 0xbfb8aa3b, v132
	v_mul_f32_e32 v133, 0xbfb8aa3b, v133
	v_mul_f32_e32 v134, 0xbfb8aa3b, v134
	v_mul_f32_e32 v135, 0xbfb8aa3b, v135
	v_mul_f32_e32 v136, 0xbfb8aa3b, v136
	v_mul_f32_e32 v137, 0xbfb8aa3b, v137
	v_mul_f32_e32 v138, 0xbfb8aa3b, v138
	v_mul_f32_e32 v139, 0xbfb8aa3b, v139
	v_exp_f32_e32 v132, v132
	v_exp_f32_e32 v133, v133
	v_exp_f32_e32 v134, v134
	v_exp_f32_e32 v135, v135
	v_exp_f32_e32 v136, v136
	v_exp_f32_e32 v137, v137
	v_exp_f32_e32 v138, v138
	v_exp_f32_e32 v139, v139
	v_add_f32_e32 v132, 1.0, v132
	v_add_f32_e32 v133, 1.0, v133
	v_add_f32_e32 v134, 1.0, v134
	v_add_f32_e32 v135, 1.0, v135
	v_add_f32_e32 v136, 1.0, v136
	v_add_f32_e32 v137, 1.0, v137
	v_add_f32_e32 v138, 1.0, v138
	v_add_f32_e32 v139, 1.0, v139
	v_rcp_f32_e32 v132, v132
	v_rcp_f32_e32 v133, v133
	v_rcp_f32_e32 v134, v134
	v_rcp_f32_e32 v135, v135
	v_rcp_f32_e32 v136, v136
	v_rcp_f32_e32 v137, v137
	v_rcp_f32_e32 v138, v138
	v_rcp_f32_e32 v139, v139
	v_max_f32_e32 v244, v244, v244
	v_max_f32_e32 v245, v245, v245
	v_max_f32_e32 v246, v246, v246
	v_max_f32_e32 v247, v247, v247
	v_max_f32_e32 v248, v248, v248
	v_max_f32_e32 v249, v249, v249
	v_max_f32_e32 v250, v250, v250
	v_max_f32_e32 v251, v251, v251
	v_med3_f32 v244, v244, s97, v226
	v_med3_f32 v245, v245, s97, v226
	v_med3_f32 v246, v246, s97, v226
	v_med3_f32 v247, v247, s97, v226
	v_med3_f32 v248, v248, s97, v226
	v_med3_f32 v249, v249, s97, v226
	v_med3_f32 v250, v250, s97, v226
	v_med3_f32 v251, v251, s97, v226
	v_mul_f32_e32 v244, 0xbfb8aa3b, v244
	v_mul_f32_e32 v245, 0xbfb8aa3b, v245
	v_mul_f32_e32 v246, 0xbfb8aa3b, v246
	v_mul_f32_e32 v247, 0xbfb8aa3b, v247
	v_mul_f32_e32 v248, 0xbfb8aa3b, v248
	v_mul_f32_e32 v249, 0xbfb8aa3b, v249
	v_mul_f32_e32 v250, 0xbfb8aa3b, v250
	v_mul_f32_e32 v251, 0xbfb8aa3b, v251
	v_exp_f32_e32 v244, v244
	v_exp_f32_e32 v245, v245
	v_exp_f32_e32 v246, v246
	v_exp_f32_e32 v247, v247
	v_exp_f32_e32 v248, v248
	v_exp_f32_e32 v249, v249
	v_exp_f32_e32 v250, v250
	v_exp_f32_e32 v251, v251
	v_add_f32_e32 v244, 1.0, v244
	v_add_f32_e32 v245, 1.0, v245
	v_add_f32_e32 v246, 1.0, v246
	v_add_f32_e32 v247, 1.0, v247
	v_add_f32_e32 v248, 1.0, v248
	v_add_f32_e32 v249, 1.0, v249
	v_add_f32_e32 v250, 1.0, v250
	v_add_f32_e32 v251, 1.0, v251
	v_pk_mul_f32 v[132:133], v[132:133], v[244:245]
	v_pk_mul_f32 v[134:135], v[134:135], v[246:247]
	v_pk_mul_f32 v[136:137], v[136:137], v[248:249]
	v_pk_mul_f32 v[138:139], v[138:139], v[250:251]
	v_pk_mul_f32 v[16:17], v[16:17], v[132:133]
	v_pk_mul_f32 v[18:19], v[18:19], v[134:135]
	v_pk_mul_f32 v[12:13], v[12:13], v[136:137]
	v_pk_mul_f32 v[14:15], v[14:15], v[138:139]
	s_waitcnt vmcnt(2)
	v_lshlrev_b32_e32 v132, 16, v228
	v_and_b32_e32 v133, 0xffff0000, v228
	v_lshlrev_b32_e32 v134, 16, v229
	v_and_b32_e32 v135, 0xffff0000, v229
	v_lshlrev_b32_e32 v136, 16, v230
	v_and_b32_e32 v137, 0xffff0000, v230
	v_lshlrev_b32_e32 v138, 16, v231
	v_and_b32_e32 v139, 0xffff0000, v231
	v_lshlrev_b32_e32 v244, 16, v232
	v_and_b32_e32 v245, 0xffff0000, v232
	v_lshlrev_b32_e32 v246, 16, v233
	v_and_b32_e32 v247, 0xffff0000, v233
	v_lshlrev_b32_e32 v248, 16, v234
	v_and_b32_e32 v249, 0xffff0000, v234
	v_lshlrev_b32_e32 v250, 16, v235
	v_and_b32_e32 v251, 0xffff0000, v235
	v_max_f32_e32 v132, v132, v132
	v_max_f32_e32 v133, v133, v133
	v_max_f32_e32 v134, v134, v134
	v_max_f32_e32 v135, v135, v135
	v_max_f32_e32 v136, v136, v136
	v_max_f32_e32 v137, v137, v137
	v_max_f32_e32 v138, v138, v138
	v_max_f32_e32 v139, v139, v139
	v_med3_f32 v132, v132, s97, v226
	v_med3_f32 v133, v133, s97, v226
	v_med3_f32 v134, v134, s97, v226
	v_med3_f32 v135, v135, s97, v226
	v_med3_f32 v136, v136, s97, v226
	v_med3_f32 v137, v137, s97, v226
	v_med3_f32 v138, v138, s97, v226
	v_med3_f32 v139, v139, s97, v226
	v_mul_f32_e32 v132, 0xbfb8aa3b, v132
	v_mul_f32_e32 v133, 0xbfb8aa3b, v133
	v_mul_f32_e32 v134, 0xbfb8aa3b, v134
	v_mul_f32_e32 v135, 0xbfb8aa3b, v135
	v_mul_f32_e32 v136, 0xbfb8aa3b, v136
	v_mul_f32_e32 v137, 0xbfb8aa3b, v137
	v_mul_f32_e32 v138, 0xbfb8aa3b, v138
	v_mul_f32_e32 v139, 0xbfb8aa3b, v139
	v_exp_f32_e32 v132, v132
	v_exp_f32_e32 v133, v133
	v_exp_f32_e32 v134, v134
	v_exp_f32_e32 v135, v135
	v_exp_f32_e32 v136, v136
	v_exp_f32_e32 v137, v137
	v_exp_f32_e32 v138, v138
	v_exp_f32_e32 v139, v139
	v_add_f32_e32 v132, 1.0, v132
	v_add_f32_e32 v133, 1.0, v133
	v_add_f32_e32 v134, 1.0, v134
	v_add_f32_e32 v135, 1.0, v135
	v_add_f32_e32 v136, 1.0, v136
	v_add_f32_e32 v137, 1.0, v137
	v_add_f32_e32 v138, 1.0, v138
	v_add_f32_e32 v139, 1.0, v139
	v_rcp_f32_e32 v132, v132
;     static __device__ __forceinline__ float e1(float x) { return 1.0f + __expf(-fminf(fmaxf(x, -60.f), 60.f)); }
;     __device__ __forceinline__ void operator()(f32x4 (&acc)[2][2][4][2], const Unit& u, int wr, int wc, int fr, int fq) const {
;     ...
;                     const int col = col0 + bj * HALF;
;                     const bf16_t* gp = proj + (size_t)row * NP + C_GATE + u.z * D + col;
;                     const u32x4 ga = *(const u32x4*)gp;
;                     float sc[8];
;                     { float a[8]; unpack8(ga, a);
; #pragma unroll
;                       for (int j = 0; j < 8; ++j) sc[j] = __builtin_amdgcn_rcpf(e1(a[j])); }
;                     if (u.z < 2) { const u32x4 gb = *(const u32x4*)(gp + D); float b[8]; unpack8(gb, b);
; #pragma unroll
;                       for (int j = 0; j < 8; ++j) sc[j] *= e1(b[j]); }
;                     f32x4 v0 = acc[ai][bj][m][0], v1 = acc[ai][bj][m][1];
;                     v0[0] *= sc[0]; v0[1] *= sc[1]; v0[2] *= sc[2]; v0[3] *= sc[3]; v1[0] *= sc[4]; v1[1] *= sc[5]; v1[2] *= sc[6]; v1[3] *= sc[7];
;                     if (u.z < 2) { acc[ai][bj][m][0] = v0; acc[ai][bj][m][1] = v1; }
	v_rcp_f32_e32 v133, v133
	v_rcp_f32_e32 v134, v134
	v_rcp_f32_e32 v135, v135
	v_rcp_f32_e32 v136, v136
	v_rcp_f32_e32 v137, v137
	v_rcp_f32_e32 v138, v138
	v_rcp_f32_e32 v139, v139
	v_max_f32_e32 v244, v244, v244
	v_max_f32_e32 v245, v245, v245
	v_max_f32_e32 v246, v246, v246
	v_max_f32_e32 v247, v247, v247
	v_max_f32_e32 v248, v248, v248
	v_max_f32_e32 v249, v249, v249
	v_max_f32_e32 v250, v250, v250
	v_max_f32_e32 v251, v251, v251
	v_med3_f32 v244, v244, s97, v226
	v_med3_f32 v245, v245, s97, v226
	v_med3_f32 v246, v246, s97, v226
	v_med3_f32 v247, v247, s97, v226
	v_med3_f32 v248, v248, s97, v226
	v_med3_f32 v249, v249, s97, v226
	v_med3_f32 v250, v250, s97, v226
	v_med3_f32 v251, v251, s97, v226
	v_mul_f32_e32 v244, 0xbfb8aa3b, v244
	v_mul_f32_e32 v245, 0xbfb8aa3b, v245
	v_mul_f32_e32 v246, 0xbfb8aa3b, v246
	v_mul_f32_e32 v247, 0xbfb8aa3b, v247
	v_mul_f32_e32 v248, 0xbfb8aa3b, v248
	v_mul_f32_e32 v249, 0xbfb8aa3b, v249
	v_mul_f32_e32 v250, 0xbfb8aa3b, v250
	v_mul_f32_e32 v251, 0xbfb8aa3b, v251
	v_exp_f32_e32 v244, v244
	v_exp_f32_e32 v245, v245
	v_exp_f32_e32 v246, v246
	v_exp_f32_e32 v247, v247
	v_exp_f32_e32 v248, v248
	v_exp_f32_e32 v249, v249
	v_exp_f32_e32 v250, v250
	v_exp_f32_e32 v251, v251
	v_add_f32_e32 v244, 1.0, v244
	v_add_f32_e32 v245, 1.0, v245
	v_add_f32_e32 v246, 1.0, v246
	v_add_f32_e32 v247, 1.0, v247
	v_add_f32_e32 v248, 1.0, v248
	v_add_f32_e32 v249, 1.0, v249
	v_add_f32_e32 v250, 1.0, v250
	v_add_f32_e32 v251, 1.0, v251
	v_pk_mul_f32 v[132:133], v[132:133], v[244:245]
	v_pk_mul_f32 v[134:135], v[134:135], v[246:247]
	v_pk_mul_f32 v[136:137], v[136:137], v[248:249]
	v_pk_mul_f32 v[138:139], v[138:139], v[250:251]
	v_pk_mul_f32 v[40:41], v[40:41], v[132:133]
	v_pk_mul_f32 v[42:43], v[42:43], v[134:135]
	v_pk_mul_f32 v[36:37], v[36:37], v[136:137]
	v_pk_mul_f32 v[38:39], v[38:39], v[138:139]
	s_waitcnt vmcnt(0)
	v_lshlrev_b32_e32 v132, 16, v236
	v_and_b32_e32 v133, 0xffff0000, v236
	v_lshlrev_b32_e32 v134, 16, v237
	v_and_b32_e32 v135, 0xffff0000, v237
	v_lshlrev_b32_e32 v136, 16, v238
	v_and_b32_e32 v137, 0xffff0000, v238
	v_lshlrev_b32_e32 v138, 16, v239
	v_and_b32_e32 v139, 0xffff0000, v239
	v_lshlrev_b32_e32 v244, 16, v240
	v_and_b32_e32 v245, 0xffff0000, v240
	v_lshlrev_b32_e32 v246, 16, v241
	v_and_b32_e32 v247, 0xffff0000, v241
	v_lshlrev_b32_e32 v248, 16, v242
	v_and_b32_e32 v249, 0xffff0000, v242
	v_lshlrev_b32_e32 v250, 16, v243
	v_and_b32_e32 v251, 0xffff0000, v243
	v_max_f32_e32 v132, v132, v132
	v_max_f32_e32 v133, v133, v133
	v_max_f32_e32 v134, v134, v134
	v_max_f32_e32 v135, v135, v135
	v_max_f32_e32 v136, v136, v136
	v_max_f32_e32 v137, v137, v137
	v_max_f32_e32 v138, v138, v138
	v_max_f32_e32 v139, v139, v139
	v_med3_f32 v132, v132, s97, v226
	v_med3_f32 v133, v133, s97, v226
	v_med3_f32 v134, v134, s97, v226
	v_med3_f32 v135, v135, s97, v226
	v_med3_f32 v136, v136, s97, v226
	v_med3_f32 v137, v137, s97, v226
	v_med3_f32 v138, v138, s97, v226
	v_med3_f32 v139, v139, s97, v226
	v_mul_f32_e32 v132, 0xbfb8aa3b, v132
	v_mul_f32_e32 v133, 0xbfb8aa3b, v133
	v_mul_f32_e32 v134, 0xbfb8aa3b, v134
	v_mul_f32_e32 v135, 0xbfb8aa3b, v135
	v_mul_f32_e32 v136, 0xbfb8aa3b, v136
	v_mul_f32_e32 v137, 0xbfb8aa3b, v137
	v_mul_f32_e32 v138, 0xbfb8aa3b, v138
	v_mul_f32_e32 v139, 0xbfb8aa3b, v139
	v_exp_f32_e32 v132, v132
	v_exp_f32_e32 v133, v133
	v_exp_f32_e32 v134, v134
	v_exp_f32_e32 v135, v135
	v_exp_f32_e32 v136, v136
	v_exp_f32_e32 v137, v137
	v_exp_f32_e32 v138, v138
	v_exp_f32_e32 v139, v139
	v_add_f32_e32 v132, 1.0, v132
	v_add_f32_e32 v133, 1.0, v133
	v_add_f32_e32 v134, 1.0, v134
	v_add_f32_e32 v135, 1.0, v135
	v_add_f32_e32 v136, 1.0, v136
	v_add_f32_e32 v137, 1.0, v137
	v_add_f32_e32 v138, 1.0, v138
	v_add_f32_e32 v139, 1.0, v139
	v_rcp_f32_e32 v132, v132
	v_rcp_f32_e32 v133, v133
	v_rcp_f32_e32 v134, v134
	v_rcp_f32_e32 v135, v135
	v_rcp_f32_e32 v136, v136
	v_rcp_f32_e32 v137, v137
	v_rcp_f32_e32 v138, v138
	v_rcp_f32_e32 v139, v139
	v_max_f32_e32 v244, v244, v244
	v_max_f32_e32 v245, v245, v245
	v_max_f32_e32 v246, v246, v246
	v_max_f32_e32 v247, v247, v247
	v_max_f32_e32 v248, v248, v248
	v_max_f32_e32 v249, v249, v249
	v_max_f32_e32 v250, v250, v250
	v_max_f32_e32 v251, v251, v251
	v_med3_f32 v244, v244, s97, v226
	v_med3_f32 v245, v245, s97, v226
	v_med3_f32 v246, v246, s97, v226
	v_med3_f32 v247, v247, s97, v226
	v_med3_f32 v248, v248, s97, v226
	v_med3_f32 v249, v249, s97, v226
	v_med3_f32 v250, v250, s97, v226
	v_med3_f32 v251, v251, s97, v226
	v_mul_f32_e32 v244, 0xbfb8aa3b, v244
	v_mul_f32_e32 v245, 0xbfb8aa3b, v245
	v_mul_f32_e32 v246, 0xbfb8aa3b, v246
	v_mul_f32_e32 v247, 0xbfb8aa3b, v247
	v_mul_f32_e32 v248, 0xbfb8aa3b, v248
	v_mul_f32_e32 v249, 0xbfb8aa3b, v249
	v_mul_f32_e32 v250, 0xbfb8aa3b, v250
	v_mul_f32_e32 v251, 0xbfb8aa3b, v251
	v_exp_f32_e32 v244, v244
	v_exp_f32_e32 v245, v245
	v_exp_f32_e32 v246, v246
	v_exp_f32_e32 v247, v247
	v_exp_f32_e32 v248, v248
	v_exp_f32_e32 v249, v249
	v_exp_f32_e32 v250, v250
	v_exp_f32_e32 v251, v251
	v_add_f32_e32 v244, 1.0, v244
	v_add_f32_e32 v245, 1.0, v245
	v_add_f32_e32 v246, 1.0, v246
	v_add_f32_e32 v247, 1.0, v247
	v_add_f32_e32 v248, 1.0, v248
	v_add_f32_e32 v249, 1.0, v249
	v_add_f32_e32 v250, 1.0, v250
	v_add_f32_e32 v251, 1.0, v251
	v_pk_mul_f32 v[132:133], v[132:133], v[244:245]
	v_pk_mul_f32 v[134:135], v[134:135], v[246:247]
	v_pk_mul_f32 v[136:137], v[136:137], v[248:249]
	v_pk_mul_f32 v[138:139], v[138:139], v[250:251]
	v_pk_mul_f32 v[8:9], v[8:9], v[132:133]
	v_pk_mul_f32 v[10:11], v[10:11], v[134:135]
	v_pk_mul_f32 v[4:5], v[4:5], v[136:137]
	v_pk_mul_f32 v[6:7], v[6:7], v[138:139]
	s_mov_b64 s[40:41], -1
	s_mov_b64 s[42:43], 0
	s_branch .Lp3_done
; __device__ __forceinline__ unsigned pk2(float lo, float hi) { f32x2_t v = {lo, hi}; bf16x2_t b = __builtin_convertvector(v, bf16x2_t); return __builtin_bit_cast(unsigned, b); }
;     static __device__ __forceinline__ float e1(float x) { return 1.0f + __expf(-fminf(fmaxf(x, -60.f), 60.f)); }
;     __device__ __forceinline__ void operator()(f32x4 (&acc)[2][2][4][2], const Unit& u, int wr, int wc, int fr, int fq) const {
;     ...
;                     const int col = col0 + bj * HALF;
;                     const bf16_t* gp = proj + (size_t)row * NP + C_GATE + u.z * D + col;
;                     const u32x4 ga = *(const u32x4*)gp;
;                     float sc[8];
;                     { float a[8]; unpack8(ga, a);
; #pragma unroll
;                       for (int j = 0; j < 8; ++j) sc[j] = __builtin_amdgcn_rcpf(e1(a[j])); }
;                     if (u.z < 2) { const u32x4 gb = *(const u32x4*)(gp + D); float b[8]; unpack8(gb, b);
; #pragma unroll
;                       for (int j = 0; j < 8; ++j) sc[j] *= e1(b[j]); }
;                     f32x4 v0 = acc[ai][bj][m][0], v1 = acc[ai][bj][m][1];
;                     v0[0] *= sc[0]; v0[1] *= sc[1]; v0[2] *= sc[2]; v0[3] *= sc[3]; v1[0] *= sc[4]; v1[1] *= sc[5]; v1[2] *= sc[6]; v1[3] *= sc[7];
;                     if (u.z < 2) { acc[ai][bj][m][0] = v0; acc[ai][bj][m][1] = v1; }
;                     else { u32x4 w; w.x = pk2(v0[0], v0[1]); w.y = pk2(v0[2], v0[3]); w.z = pk2(v1[0], v1[1]); w.w = pk2(v1[2], v1[3]); *(u32x4*)(YB + (size_t)row * D + col) = w; }
.Lp3_store:
	s_mov_b64 s[8:9], 0x0
	v_lshl_add_u64 v[156:157], v[152:153], 0, s[8:9]
	global_load_dwordx4 v[162:165], v[156:157], off offset:-4096
	s_mov_b64 s[8:9], 0x0
	v_lshl_add_u64 v[156:157], v[152:153], 0, s[8:9]
	global_load_dwordx4 v[170:173], v[156:157], off offset:-3840
	s_mov_b64 s[8:9], 0x88000
	v_lshl_add_u64 v[156:157], v[152:153], 0, s[8:9]
	global_load_dwordx4 v[178:181], v[156:157], off offset:-4096
	s_mov_b64 s[8:9], 0x88000
	v_lshl_add_u64 v[156:157], v[152:153], 0, s[8:9]
	global_load_dwordx4 v[186:189], v[156:157], off offset:-3840
	s_mov_b64 s[8:9], 0x110000
	v_lshl_add_u64 v[156:157], v[152:153], 0, s[8:9]
	global_load_dwordx4 v[194:197], v[156:157], off offset:-4096
	s_mov_b64 s[8:9], 0x110000
	v_lshl_add_u64 v[156:157], v[152:153], 0, s[8:9]
	global_load_dwordx4 v[206:209], v[156:157], off offset:-3840
	s_mov_b64 s[8:9], 0x198000
	v_lshl_add_u64 v[156:157], v[152:153], 0, s[8:9]
	global_load_dwordx4 v[228:231], v[156:157], off offset:-4096
	s_mov_b64 s[8:9], 0x198000
	v_lshl_add_u64 v[156:157], v[152:153], 0, s[8:9]
	global_load_dwordx4 v[236:239], v[156:157], off offset:-3840
	s_waitcnt vmcnt(7)
	v_lshlrev_b32_e32 v132, 16, v162
	v_and_b32_e32 v133, 0xffff0000, v162
	v_lshlrev_b32_e32 v134, 16, v163
	v_and_b32_e32 v135, 0xffff0000, v163
	v_lshlrev_b32_e32 v136, 16, v164
	v_and_b32_e32 v137, 0xffff0000, v164
	v_lshlrev_b32_e32 v138, 16, v165
	v_and_b32_e32 v139, 0xffff0000, v165
	s_mov_b64 s[8:9], 0x440000
	v_lshl_add_u64 v[156:157], v[152:153], 0, s[8:9]
	global_load_dwordx4 v[162:165], v[156:157], off offset:-4096
	v_max_f32_e32 v132, v132, v132
	v_max_f32_e32 v133, v133, v133
	v_max_f32_e32 v134, v134, v134
	v_max_f32_e32 v135, v135, v135
	v_max_f32_e32 v136, v136, v136
	v_max_f32_e32 v137, v137, v137
	v_max_f32_e32 v138, v138, v138
	v_max_f32_e32 v139, v139, v139
	v_med3_f32 v132, v132, s97, v226
	v_med3_f32 v133, v133, s97, v226
	v_med3_f32 v134, v134, s97, v226
	v_med3_f32 v135, v135, s97, v226
	v_med3_f32 v136, v136, s97, v226
	v_med3_f32 v137, v137, s97, v226
	v_med3_f32 v138, v138, s97, v226
	v_med3_f32 v139, v139, s97, v226
	v_mul_f32_e32 v132, 0xbfb8aa3b, v132
	v_mul_f32_e32 v133, 0xbfb8aa3b, v133
	v_mul_f32_e32 v134, 0xbfb8aa3b, v134
	v_mul_f32_e32 v135, 0xbfb8aa3b, v135
	v_mul_f32_e32 v136, 0xbfb8aa3b, v136
	v_mul_f32_e32 v137, 0xbfb8aa3b, v137
	v_mul_f32_e32 v138, 0xbfb8aa3b, v138
	v_mul_f32_e32 v139, 0xbfb8aa3b, v139
	v_exp_f32_e32 v132, v132
	v_exp_f32_e32 v133, v133
	v_exp_f32_e32 v134, v134
	v_exp_f32_e32 v135, v135
	v_exp_f32_e32 v136, v136
	v_exp_f32_e32 v137, v137
	v_exp_f32_e32 v138, v138
	v_exp_f32_e32 v139, v139
	v_add_f32_e32 v132, 1.0, v132
	v_add_f32_e32 v133, 1.0, v133
	v_add_f32_e32 v134, 1.0, v134
	v_add_f32_e32 v135, 1.0, v135
	v_add_f32_e32 v136, 1.0, v136
	v_add_f32_e32 v137, 1.0, v137
	v_add_f32_e32 v138, 1.0, v138
	v_add_f32_e32 v139, 1.0, v139
	v_rcp_f32_e32 v132, v132
	v_rcp_f32_e32 v133, v133
	v_rcp_f32_e32 v134, v134
	v_rcp_f32_e32 v135, v135
	v_rcp_f32_e32 v136, v136
	v_rcp_f32_e32 v137, v137
	v_rcp_f32_e32 v138, v138
	v_rcp_f32_e32 v139, v139
	v_pk_mul_f32 v[132:133], v[128:129], v[132:133]
	v_pk_mul_f32 v[134:135], v[130:131], v[134:135]
	v_pk_mul_f32 v[136:137], v[124:125], v[136:137]
	v_pk_mul_f32 v[138:139], v[126:127], v[138:139]
	v_cvt_pk_bf16_f32 v244, v132, v133
	v_cvt_pk_bf16_f32 v245, v134, v135
	v_cvt_pk_bf16_f32 v246, v136, v137
	v_cvt_pk_bf16_f32 v247, v138, v139
	s_mov_b64 s[8:9], 0x0
	v_lshl_add_u64 v[156:157], v[154:155], 0, s[8:9]
	global_store_dwordx4 v[156:157], v[244:247], off offset:0
	s_waitcnt vmcnt(8)
	v_lshlrev_b32_e32 v132, 16, v170
	v_and_b32_e32 v133, 0xffff0000, v170
	v_lshlrev_b32_e32 v134, 16, v171
	v_and_b32_e32 v135, 0xffff0000, v171
	v_lshlrev_b32_e32 v136, 16, v172
	v_and_b32_e32 v137, 0xffff0000, v172
	v_lshlrev_b32_e32 v138, 16, v173
	v_and_b32_e32 v139, 0xffff0000, v173
	s_mov_b64 s[8:9], 0x440000
	v_lshl_add_u64 v[156:157], v[152:153], 0, s[8:9]
	global_load_dwordx4 v[170:173], v[156:157], off offset:-3840
	v_max_f32_e32 v132, v132, v132
	v_max_f32_e32 v133, v133, v133
	v_max_f32_e32 v134, v134, v134
	v_max_f32_e32 v135, v135, v135
	v_max_f32_e32 v136, v136, v136
	v_max_f32_e32 v137, v137, v137
	v_max_f32_e32 v138, v138, v138
	v_max_f32_e32 v139, v139, v139
	v_med3_f32 v132, v132, s97, v226
	v_med3_f32 v133, v133, s97, v226
	v_med3_f32 v134, v134, s97, v226
	v_med3_f32 v135, v135, s97, v226
	v_med3_f32 v136, v136, s97, v226
	v_med3_f32 v137, v137, s97, v226
	v_med3_f32 v138, v138, s97, v226
	v_med3_f32 v139, v139, s97, v226
	v_mul_f32_e32 v132, 0xbfb8aa3b, v132
	v_mul_f32_e32 v133, 0xbfb8aa3b, v133
	v_mul_f32_e32 v134, 0xbfb8aa3b, v134
	v_mul_f32_e32 v135, 0xbfb8aa3b, v135
	v_mul_f32_e32 v136, 0xbfb8aa3b, v136
	v_mul_f32_e32 v137, 0xbfb8aa3b, v137
	v_mul_f32_e32 v138, 0xbfb8aa3b, v138
	v_mul_f32_e32 v139, 0xbfb8aa3b, v139
	v_exp_f32_e32 v132, v132
	v_exp_f32_e32 v133, v133
	v_exp_f32_e32 v134, v134
	v_exp_f32_e32 v135, v135
	v_exp_f32_e32 v136, v136
	v_exp_f32_e32 v137, v137
	v_exp_f32_e32 v138, v138
	v_exp_f32_e32 v139, v139
	v_add_f32_e32 v132, 1.0, v132
	v_add_f32_e32 v133, 1.0, v133
	v_add_f32_e32 v134, 1.0, v134
	v_add_f32_e32 v135, 1.0, v135
	v_add_f32_e32 v136, 1.0, v136
	v_add_f32_e32 v137, 1.0, v137
	v_add_f32_e32 v138, 1.0, v138
	v_add_f32_e32 v139, 1.0, v139
	v_rcp_f32_e32 v132, v132
	v_rcp_f32_e32 v133, v133
	v_rcp_f32_e32 v134, v134
	v_rcp_f32_e32 v135, v135
	v_rcp_f32_e32 v136, v136
	v_rcp_f32_e32 v137, v137
	v_rcp_f32_e32 v138, v138
	v_rcp_f32_e32 v139, v139
	v_pk_mul_f32 v[132:133], v[96:97], v[132:133]
	v_pk_mul_f32 v[134:135], v[98:99], v[134:135]
	v_pk_mul_f32 v[136:137], v[92:93], v[136:137]
	v_pk_mul_f32 v[138:139], v[94:95], v[138:139]
	v_cvt_pk_bf16_f32 v248, v132, v133
	v_cvt_pk_bf16_f32 v249, v134, v135
	v_cvt_pk_bf16_f32 v250, v136, v137
	v_cvt_pk_bf16_f32 v251, v138, v139
	s_mov_b64 s[8:9], 0x0
	v_lshl_add_u64 v[156:157], v[154:155], 0, s[8:9]
	global_store_dwordx4 v[156:157], v[248:251], off offset:256
	s_waitcnt vmcnt(9)
; __device__ __forceinline__ unsigned pk2(float lo, float hi) { f32x2_t v = {lo, hi}; bf16x2_t b = __builtin_convertvector(v, bf16x2_t); return __builtin_bit_cast(unsigned, b); }
;     static __device__ __forceinline__ float e1(float x) { return 1.0f + __expf(-fminf(fmaxf(x, -60.f), 60.f)); }
;     __device__ __forceinline__ void operator()(f32x4 (&acc)[2][2][4][2], const Unit& u, int wr, int wc, int fr, int fq) const {
;     ...
;                     const int col = col0 + bj * HALF;
;                     const bf16_t* gp = proj + (size_t)row * NP + C_GATE + u.z * D + col;
;                     const u32x4 ga = *(const u32x4*)gp;
;                     float sc[8];
;                     { float a[8]; unpack8(ga, a);
; #pragma unroll
;                       for (int j = 0; j < 8; ++j) sc[j] = __builtin_amdgcn_rcpf(e1(a[j])); }
;                     if (u.z < 2) { const u32x4 gb = *(const u32x4*)(gp + D); float b[8]; unpack8(gb, b);
; #pragma unroll
;                       for (int j = 0; j < 8; ++j) sc[j] *= e1(b[j]); }
;                     f32x4 v0 = acc[ai][bj][m][0], v1 = acc[ai][bj][m][1];
;                     v0[0] *= sc[0]; v0[1] *= sc[1]; v0[2] *= sc[2]; v0[3] *= sc[3]; v1[0] *= sc[4]; v1[1] *= sc[5]; v1[2] *= sc[6]; v1[3] *= sc[7];
;                     if (u.z < 2) { acc[ai][bj][m][0] = v0; acc[ai][bj][m][1] = v1; }
;                     else { u32x4 w; w.x = pk2(v0[0], v0[1]); w.y = pk2(v0[2], v0[3]); w.z = pk2(v1[0], v1[1]); w.w = pk2(v1[2], v1[3]); *(u32x4*)(YB + (size_t)row * D + col) = w; }
	v_lshlrev_b32_e32 v132, 16, v178
	v_and_b32_e32 v133, 0xffff0000, v178
	v_lshlrev_b32_e32 v134, 16, v179
	v_and_b32_e32 v135, 0xffff0000, v179
	v_lshlrev_b32_e32 v136, 16, v180
	v_and_b32_e32 v137, 0xffff0000, v180
	v_lshlrev_b32_e32 v138, 16, v181
	v_and_b32_e32 v139, 0xffff0000, v181
	s_mov_b64 s[8:9], 0x4c8000
	v_lshl_add_u64 v[156:157], v[152:153], 0, s[8:9]
	global_load_dwordx4 v[178:181], v[156:157], off offset:-4096
	v_max_f32_e32 v132, v132, v132
	v_max_f32_e32 v133, v133, v133
	v_max_f32_e32 v134, v134, v134
	v_max_f32_e32 v135, v135, v135
	v_max_f32_e32 v136, v136, v136
	v_max_f32_e32 v137, v137, v137
	v_max_f32_e32 v138, v138, v138
	v_max_f32_e32 v139, v139, v139
	v_med3_f32 v132, v132, s97, v226
	v_med3_f32 v133, v133, s97, v226
	v_med3_f32 v134, v134, s97, v226
	v_med3_f32 v135, v135, s97, v226
	v_med3_f32 v136, v136, s97, v226
	v_med3_f32 v137, v137, s97, v226
	v_med3_f32 v138, v138, s97, v226
	v_med3_f32 v139, v139, s97, v226
	v_mul_f32_e32 v132, 0xbfb8aa3b, v132
	v_mul_f32_e32 v133, 0xbfb8aa3b, v133
	v_mul_f32_e32 v134, 0xbfb8aa3b, v134
	v_mul_f32_e32 v135, 0xbfb8aa3b, v135
	v_mul_f32_e32 v136, 0xbfb8aa3b, v136
	v_mul_f32_e32 v137, 0xbfb8aa3b, v137
	v_mul_f32_e32 v138, 0xbfb8aa3b, v138
	v_mul_f32_e32 v139, 0xbfb8aa3b, v139
	v_exp_f32_e32 v132, v132
	v_exp_f32_e32 v133, v133
	v_exp_f32_e32 v134, v134
	v_exp_f32_e32 v135, v135
	v_exp_f32_e32 v136, v136
	v_exp_f32_e32 v137, v137
	v_exp_f32_e32 v138, v138
	v_exp_f32_e32 v139, v139
	v_add_f32_e32 v132, 1.0, v132
	v_add_f32_e32 v133, 1.0, v133
	v_add_f32_e32 v134, 1.0, v134
	v_add_f32_e32 v135, 1.0, v135
	v_add_f32_e32 v136, 1.0, v136
	v_add_f32_e32 v137, 1.0, v137
	v_add_f32_e32 v138, 1.0, v138
	v_add_f32_e32 v139, 1.0, v139
	v_rcp_f32_e32 v132, v132
	v_rcp_f32_e32 v133, v133
	v_rcp_f32_e32 v134, v134
	v_rcp_f32_e32 v135, v135
	v_rcp_f32_e32 v136, v136
	v_rcp_f32_e32 v137, v137
	v_rcp_f32_e32 v138, v138
	v_rcp_f32_e32 v139, v139
	v_pk_mul_f32 v[132:133], v[120:121], v[132:133]
	v_pk_mul_f32 v[134:135], v[122:123], v[134:135]
	v_pk_mul_f32 v[136:137], v[116:117], v[136:137]
	v_pk_mul_f32 v[138:139], v[118:119], v[138:139]
	v_cvt_pk_bf16_f32 v244, v132, v133
	v_cvt_pk_bf16_f32 v245, v134, v135
	v_cvt_pk_bf16_f32 v246, v136, v137
	v_cvt_pk_bf16_f32 v247, v138, v139
	s_mov_b64 s[8:9], 0x10000
	v_lshl_add_u64 v[156:157], v[154:155], 0, s[8:9]
	global_store_dwordx4 v[156:157], v[244:247], off offset:0
	s_waitcnt vmcnt(10)
	v_lshlrev_b32_e32 v132, 16, v186
	v_and_b32_e32 v133, 0xffff0000, v186
	v_lshlrev_b32_e32 v134, 16, v187
	v_and_b32_e32 v135, 0xffff0000, v187
	v_lshlrev_b32_e32 v136, 16, v188
	v_and_b32_e32 v137, 0xffff0000, v188
	v_lshlrev_b32_e32 v138, 16, v189
	v_and_b32_e32 v139, 0xffff0000, v189
	s_mov_b64 s[8:9], 0x4c8000
	v_lshl_add_u64 v[156:157], v[152:153], 0, s[8:9]
	global_load_dwordx4 v[186:189], v[156:157], off offset:-3840
	v_max_f32_e32 v132, v132, v132
	v_max_f32_e32 v133, v133, v133
	v_max_f32_e32 v134, v134, v134
	v_max_f32_e32 v135, v135, v135
	v_max_f32_e32 v136, v136, v136
	v_max_f32_e32 v137, v137, v137
	v_max_f32_e32 v138, v138, v138
	v_max_f32_e32 v139, v139, v139
	v_med3_f32 v132, v132, s97, v226
	v_med3_f32 v133, v133, s97, v226
	v_med3_f32 v134, v134, s97, v226
	v_med3_f32 v135, v135, s97, v226
	v_med3_f32 v136, v136, s97, v226
	v_med3_f32 v137, v137, s97, v226
	v_med3_f32 v138, v138, s97, v226
	v_med3_f32 v139, v139, s97, v226
	v_mul_f32_e32 v132, 0xbfb8aa3b, v132
	v_mul_f32_e32 v133, 0xbfb8aa3b, v133
	v_mul_f32_e32 v134, 0xbfb8aa3b, v134
	v_mul_f32_e32 v135, 0xbfb8aa3b, v135
	v_mul_f32_e32 v136, 0xbfb8aa3b, v136
	v_mul_f32_e32 v137, 0xbfb8aa3b, v137
	v_mul_f32_e32 v138, 0xbfb8aa3b, v138
	v_mul_f32_e32 v139, 0xbfb8aa3b, v139
	v_exp_f32_e32 v132, v132
	v_exp_f32_e32 v133, v133
	v_exp_f32_e32 v134, v134
	v_exp_f32_e32 v135, v135
	v_exp_f32_e32 v136, v136
	v_exp_f32_e32 v137, v137
	v_exp_f32_e32 v138, v138
	v_exp_f32_e32 v139, v139
	v_add_f32_e32 v132, 1.0, v132
	v_add_f32_e32 v133, 1.0, v133
	v_add_f32_e32 v134, 1.0, v134
	v_add_f32_e32 v135, 1.0, v135
	v_add_f32_e32 v136, 1.0, v136
	v_add_f32_e32 v137, 1.0, v137
	v_add_f32_e32 v138, 1.0, v138
	v_add_f32_e32 v139, 1.0, v139
	v_rcp_f32_e32 v132, v132
	v_rcp_f32_e32 v133, v133
	v_rcp_f32_e32 v134, v134
	v_rcp_f32_e32 v135, v135
	v_rcp_f32_e32 v136, v136
	v_rcp_f32_e32 v137, v137
	v_rcp_f32_e32 v138, v138
	v_rcp_f32_e32 v139, v139
	v_pk_mul_f32 v[132:133], v[88:89], v[132:133]
	v_pk_mul_f32 v[134:135], v[90:91], v[134:135]
	v_pk_mul_f32 v[136:137], v[84:85], v[136:137]
	v_pk_mul_f32 v[138:139], v[86:87], v[138:139]
	v_cvt_pk_bf16_f32 v248, v132, v133
	v_cvt_pk_bf16_f32 v249, v134, v135
	v_cvt_pk_bf16_f32 v250, v136, v137
	v_cvt_pk_bf16_f32 v251, v138, v139
	s_mov_b64 s[8:9], 0x10000
	v_lshl_add_u64 v[156:157], v[154:155], 0, s[8:9]
	global_store_dwordx4 v[156:157], v[248:251], off offset:256
	s_waitcnt vmcnt(11)
; __device__ __forceinline__ unsigned pk2(float lo, float hi) { f32x2_t v = {lo, hi}; bf16x2_t b = __builtin_convertvector(v, bf16x2_t); return __builtin_bit_cast(unsigned, b); }
;     static __device__ __forceinline__ float e1(float x) { return 1.0f + __expf(-fminf(fmaxf(x, -60.f), 60.f)); }
;     __device__ __forceinline__ void operator()(f32x4 (&acc)[2][2][4][2], const Unit& u, int wr, int wc, int fr, int fq) const {
;     ...
;                     const int col = col0 + bj * HALF;
;                     const bf16_t* gp = proj + (size_t)row * NP + C_GATE + u.z * D + col;
;                     const u32x4 ga = *(const u32x4*)gp;
;                     float sc[8];
;                     { float a[8]; unpack8(ga, a);
; #pragma unroll
;                       for (int j = 0; j < 8; ++j) sc[j] = __builtin_amdgcn_rcpf(e1(a[j])); }
;                     if (u.z < 2) { const u32x4 gb = *(const u32x4*)(gp + D); float b[8]; unpack8(gb, b);
; #pragma unroll
;                       for (int j = 0; j < 8; ++j) sc[j] *= e1(b[j]); }
;                     f32x4 v0 = acc[ai][bj][m][0], v1 = acc[ai][bj][m][1];
;                     v0[0] *= sc[0]; v0[1] *= sc[1]; v0[2] *= sc[2]; v0[3] *= sc[3]; v1[0] *= sc[4]; v1[1] *= sc[5]; v1[2] *= sc[6]; v1[3] *= sc[7];
;                     if (u.z < 2) { acc[ai][bj][m][0] = v0; acc[ai][bj][m][1] = v1; }
;                     else { u32x4 w; w.x = pk2(v0[0], v0[1]); w.y = pk2(v0[2], v0[3]); w.z = pk2(v1[0], v1[1]); w.w = pk2(v1[2], v1[3]); *(u32x4*)(YB + (size_t)row * D + col) = w; }
	v_lshlrev_b32_e32 v132, 16, v194
	v_and_b32_e32 v133, 0xffff0000, v194
	v_lshlrev_b32_e32 v134, 16, v195
	v_and_b32_e32 v135, 0xffff0000, v195
	v_lshlrev_b32_e32 v136, 16, v196
	v_and_b32_e32 v137, 0xffff0000, v196
	v_lshlrev_b32_e32 v138, 16, v197
	v_and_b32_e32 v139, 0xffff0000, v197
	s_mov_b64 s[8:9], 0x550000
	v_lshl_add_u64 v[156:157], v[152:153], 0, s[8:9]
	global_load_dwordx4 v[194:197], v[156:157], off offset:-4096
	v_max_f32_e32 v132, v132, v132
	v_max_f32_e32 v133, v133, v133
	v_max_f32_e32 v134, v134, v134
	v_max_f32_e32 v135, v135, v135
	v_max_f32_e32 v136, v136, v136
	v_max_f32_e32 v137, v137, v137
	v_max_f32_e32 v138, v138, v138
	v_max_f32_e32 v139, v139, v139
	v_med3_f32 v132, v132, s97, v226
	v_med3_f32 v133, v133, s97, v226
	v_med3_f32 v134, v134, s97, v226
	v_med3_f32 v135, v135, s97, v226
	v_med3_f32 v136, v136, s97, v226
	v_med3_f32 v137, v137, s97, v226
	v_med3_f32 v138, v138, s97, v226
	v_med3_f32 v139, v139, s97, v226
	v_mul_f32_e32 v132, 0xbfb8aa3b, v132
	v_mul_f32_e32 v133, 0xbfb8aa3b, v133
	v_mul_f32_e32 v134, 0xbfb8aa3b, v134
	v_mul_f32_e32 v135, 0xbfb8aa3b, v135
	v_mul_f32_e32 v136, 0xbfb8aa3b, v136
	v_mul_f32_e32 v137, 0xbfb8aa3b, v137
	v_mul_f32_e32 v138, 0xbfb8aa3b, v138
	v_mul_f32_e32 v139, 0xbfb8aa3b, v139
	v_exp_f32_e32 v132, v132
	v_exp_f32_e32 v133, v133
	v_exp_f32_e32 v134, v134
	v_exp_f32_e32 v135, v135
	v_exp_f32_e32 v136, v136
	v_exp_f32_e32 v137, v137
	v_exp_f32_e32 v138, v138
	v_exp_f32_e32 v139, v139
	v_add_f32_e32 v132, 1.0, v132
	v_add_f32_e32 v133, 1.0, v133
	v_add_f32_e32 v134, 1.0, v134
	v_add_f32_e32 v135, 1.0, v135
	v_add_f32_e32 v136, 1.0, v136
	v_add_f32_e32 v137, 1.0, v137
	v_add_f32_e32 v138, 1.0, v138
	v_add_f32_e32 v139, 1.0, v139
	v_rcp_f32_e32 v132, v132
	v_rcp_f32_e32 v133, v133
	v_rcp_f32_e32 v134, v134
	v_rcp_f32_e32 v135, v135
	v_rcp_f32_e32 v136, v136
	v_rcp_f32_e32 v137, v137
	v_rcp_f32_e32 v138, v138
	v_rcp_f32_e32 v139, v139
	v_pk_mul_f32 v[132:133], v[112:113], v[132:133]
	v_pk_mul_f32 v[134:135], v[114:115], v[134:135]
	v_pk_mul_f32 v[136:137], v[108:109], v[136:137]
	v_pk_mul_f32 v[138:139], v[110:111], v[138:139]
	v_cvt_pk_bf16_f32 v244, v132, v133
	v_cvt_pk_bf16_f32 v245, v134, v135
	v_cvt_pk_bf16_f32 v246, v136, v137
	v_cvt_pk_bf16_f32 v247, v138, v139
	s_mov_b64 s[8:9], 0x20000
	v_lshl_add_u64 v[156:157], v[154:155], 0, s[8:9]
	global_store_dwordx4 v[156:157], v[244:247], off offset:0
	s_waitcnt vmcnt(12)
	v_lshlrev_b32_e32 v132, 16, v206
	v_and_b32_e32 v133, 0xffff0000, v206
	v_lshlrev_b32_e32 v134, 16, v207
	v_and_b32_e32 v135, 0xffff0000, v207
	v_lshlrev_b32_e32 v136, 16, v208
	v_and_b32_e32 v137, 0xffff0000, v208
	v_lshlrev_b32_e32 v138, 16, v209
	v_and_b32_e32 v139, 0xffff0000, v209
	s_mov_b64 s[8:9], 0x550000
	v_lshl_add_u64 v[156:157], v[152:153], 0, s[8:9]
	global_load_dwordx4 v[206:209], v[156:157], off offset:-3840
	v_max_f32_e32 v132, v132, v132
	v_max_f32_e32 v133, v133, v133
	v_max_f32_e32 v134, v134, v134
	v_max_f32_e32 v135, v135, v135
	v_max_f32_e32 v136, v136, v136
	v_max_f32_e32 v137, v137, v137
	v_max_f32_e32 v138, v138, v138
	v_max_f32_e32 v139, v139, v139
	v_med3_f32 v132, v132, s97, v226
	v_med3_f32 v133, v133, s97, v226
	v_med3_f32 v134, v134, s97, v226
	v_med3_f32 v135, v135, s97, v226
	v_med3_f32 v136, v136, s97, v226
	v_med3_f32 v137, v137, s97, v226
	v_med3_f32 v138, v138, s97, v226
	v_med3_f32 v139, v139, s97, v226
	v_mul_f32_e32 v132, 0xbfb8aa3b, v132
	v_mul_f32_e32 v133, 0xbfb8aa3b, v133
	v_mul_f32_e32 v134, 0xbfb8aa3b, v134
	v_mul_f32_e32 v135, 0xbfb8aa3b, v135
	v_mul_f32_e32 v136, 0xbfb8aa3b, v136
	v_mul_f32_e32 v137, 0xbfb8aa3b, v137
	v_mul_f32_e32 v138, 0xbfb8aa3b, v138
	v_mul_f32_e32 v139, 0xbfb8aa3b, v139
	v_exp_f32_e32 v132, v132
	v_exp_f32_e32 v133, v133
	v_exp_f32_e32 v134, v134
	v_exp_f32_e32 v135, v135
	v_exp_f32_e32 v136, v136
	v_exp_f32_e32 v137, v137
	v_exp_f32_e32 v138, v138
	v_exp_f32_e32 v139, v139
	v_add_f32_e32 v132, 1.0, v132
	v_add_f32_e32 v133, 1.0, v133
	v_add_f32_e32 v134, 1.0, v134
	v_add_f32_e32 v135, 1.0, v135
	v_add_f32_e32 v136, 1.0, v136
	v_add_f32_e32 v137, 1.0, v137
	v_add_f32_e32 v138, 1.0, v138
	v_add_f32_e32 v139, 1.0, v139
	v_rcp_f32_e32 v132, v132
	v_rcp_f32_e32 v133, v133
	v_rcp_f32_e32 v134, v134
	v_rcp_f32_e32 v135, v135
	v_rcp_f32_e32 v136, v136
	v_rcp_f32_e32 v137, v137
	v_rcp_f32_e32 v138, v138
	v_rcp_f32_e32 v139, v139
	v_pk_mul_f32 v[132:133], v[80:81], v[132:133]
	v_pk_mul_f32 v[134:135], v[82:83], v[134:135]
	v_pk_mul_f32 v[136:137], v[76:77], v[136:137]
	v_pk_mul_f32 v[138:139], v[78:79], v[138:139]
	v_cvt_pk_bf16_f32 v248, v132, v133
	v_cvt_pk_bf16_f32 v249, v134, v135
	v_cvt_pk_bf16_f32 v250, v136, v137
	v_cvt_pk_bf16_f32 v251, v138, v139
	s_mov_b64 s[8:9], 0x20000
	v_lshl_add_u64 v[156:157], v[154:155], 0, s[8:9]
	global_store_dwordx4 v[156:157], v[248:251], off offset:256
	s_waitcnt vmcnt(13)
; __device__ __forceinline__ unsigned pk2(float lo, float hi) { f32x2_t v = {lo, hi}; bf16x2_t b = __builtin_convertvector(v, bf16x2_t); return __builtin_bit_cast(unsigned, b); }
;     static __device__ __forceinline__ float e1(float x) { return 1.0f + __expf(-fminf(fmaxf(x, -60.f), 60.f)); }
;     __device__ __forceinline__ void operator()(f32x4 (&acc)[2][2][4][2], const Unit& u, int wr, int wc, int fr, int fq) const {
;     ...
;                     const int col = col0 + bj * HALF;
;                     const bf16_t* gp = proj + (size_t)row * NP + C_GATE + u.z * D + col;
;                     const u32x4 ga = *(const u32x4*)gp;
;                     float sc[8];
;                     { float a[8]; unpack8(ga, a);
; #pragma unroll
;                       for (int j = 0; j < 8; ++j) sc[j] = __builtin_amdgcn_rcpf(e1(a[j])); }
;                     if (u.z < 2) { const u32x4 gb = *(const u32x4*)(gp + D); float b[8]; unpack8(gb, b);
; #pragma unroll
;                       for (int j = 0; j < 8; ++j) sc[j] *= e1(b[j]); }
;                     f32x4 v0 = acc[ai][bj][m][0], v1 = acc[ai][bj][m][1];
;                     v0[0] *= sc[0]; v0[1] *= sc[1]; v0[2] *= sc[2]; v0[3] *= sc[3]; v1[0] *= sc[4]; v1[1] *= sc[5]; v1[2] *= sc[6]; v1[3] *= sc[7];
;                     if (u.z < 2) { acc[ai][bj][m][0] = v0; acc[ai][bj][m][1] = v1; }
;                     else { u32x4 w; w.x = pk2(v0[0], v0[1]); w.y = pk2(v0[2], v0[3]); w.z = pk2(v1[0], v1[1]); w.w = pk2(v1[2], v1[3]); *(u32x4*)(YB + (size_t)row * D + col) = w; }
	v_lshlrev_b32_e32 v132, 16, v228
	v_and_b32_e32 v133, 0xffff0000, v228
	v_lshlrev_b32_e32 v134, 16, v229
	v_and_b32_e32 v135, 0xffff0000, v229
	v_lshlrev_b32_e32 v136, 16, v230
	v_and_b32_e32 v137, 0xffff0000, v230
	v_lshlrev_b32_e32 v138, 16, v231
	v_and_b32_e32 v139, 0xffff0000, v231
	s_mov_b64 s[8:9], 0x5d8000
	v_lshl_add_u64 v[156:157], v[152:153], 0, s[8:9]
	global_load_dwordx4 v[228:231], v[156:157], off offset:-4096
	v_max_f32_e32 v132, v132, v132
	v_max_f32_e32 v133, v133, v133
	v_max_f32_e32 v134, v134, v134
	v_max_f32_e32 v135, v135, v135
	v_max_f32_e32 v136, v136, v136
	v_max_f32_e32 v137, v137, v137
	v_max_f32_e32 v138, v138, v138
	v_max_f32_e32 v139, v139, v139
	v_med3_f32 v132, v132, s97, v226
	v_med3_f32 v133, v133, s97, v226
	v_med3_f32 v134, v134, s97, v226
	v_med3_f32 v135, v135, s97, v226
	v_med3_f32 v136, v136, s97, v226
	v_med3_f32 v137, v137, s97, v226
	v_med3_f32 v138, v138, s97, v226
	v_med3_f32 v139, v139, s97, v226
	v_mul_f32_e32 v132, 0xbfb8aa3b, v132
	v_mul_f32_e32 v133, 0xbfb8aa3b, v133
	v_mul_f32_e32 v134, 0xbfb8aa3b, v134
	v_mul_f32_e32 v135, 0xbfb8aa3b, v135
	v_mul_f32_e32 v136, 0xbfb8aa3b, v136
	v_mul_f32_e32 v137, 0xbfb8aa3b, v137
	v_mul_f32_e32 v138, 0xbfb8aa3b, v138
	v_mul_f32_e32 v139, 0xbfb8aa3b, v139
	v_exp_f32_e32 v132, v132
	v_exp_f32_e32 v133, v133
	v_exp_f32_e32 v134, v134
	v_exp_f32_e32 v135, v135
	v_exp_f32_e32 v136, v136
	v_exp_f32_e32 v137, v137
	v_exp_f32_e32 v138, v138
	v_exp_f32_e32 v139, v139
	v_add_f32_e32 v132, 1.0, v132
	v_add_f32_e32 v133, 1.0, v133
	v_add_f32_e32 v134, 1.0, v134
	v_add_f32_e32 v135, 1.0, v135
	v_add_f32_e32 v136, 1.0, v136
	v_add_f32_e32 v137, 1.0, v137
	v_add_f32_e32 v138, 1.0, v138
	v_add_f32_e32 v139, 1.0, v139
	v_rcp_f32_e32 v132, v132
	v_rcp_f32_e32 v133, v133
	v_rcp_f32_e32 v134, v134
	v_rcp_f32_e32 v135, v135
	v_rcp_f32_e32 v136, v136
	v_rcp_f32_e32 v137, v137
	v_rcp_f32_e32 v138, v138
	v_rcp_f32_e32 v139, v139
	v_pk_mul_f32 v[132:133], v[104:105], v[132:133]
	v_pk_mul_f32 v[134:135], v[106:107], v[134:135]
	v_pk_mul_f32 v[136:137], v[100:101], v[136:137]
	v_pk_mul_f32 v[138:139], v[102:103], v[138:139]
	v_cvt_pk_bf16_f32 v244, v132, v133
	v_cvt_pk_bf16_f32 v245, v134, v135
	v_cvt_pk_bf16_f32 v246, v136, v137
	v_cvt_pk_bf16_f32 v247, v138, v139
	s_mov_b64 s[8:9], 0x30000
	v_lshl_add_u64 v[156:157], v[154:155], 0, s[8:9]
	global_store_dwordx4 v[156:157], v[244:247], off offset:0
	s_waitcnt vmcnt(14)
	v_lshlrev_b32_e32 v132, 16, v236
	v_and_b32_e32 v133, 0xffff0000, v236
	v_lshlrev_b32_e32 v134, 16, v237
	v_and_b32_e32 v135, 0xffff0000, v237
	v_lshlrev_b32_e32 v136, 16, v238
	v_and_b32_e32 v137, 0xffff0000, v238
	v_lshlrev_b32_e32 v138, 16, v239
	v_and_b32_e32 v139, 0xffff0000, v239
	s_mov_b64 s[8:9], 0x5d8000
	v_lshl_add_u64 v[156:157], v[152:153], 0, s[8:9]
	global_load_dwordx4 v[236:239], v[156:157], off offset:-3840
	v_max_f32_e32 v132, v132, v132
	v_max_f32_e32 v133, v133, v133
	v_max_f32_e32 v134, v134, v134
	v_max_f32_e32 v135, v135, v135
	v_max_f32_e32 v136, v136, v136
	v_max_f32_e32 v137, v137, v137
	v_max_f32_e32 v138, v138, v138
	v_max_f32_e32 v139, v139, v139
	v_med3_f32 v132, v132, s97, v226
	v_med3_f32 v133, v133, s97, v226
	v_med3_f32 v134, v134, s97, v226
	v_med3_f32 v135, v135, s97, v226
	v_med3_f32 v136, v136, s97, v226
	v_med3_f32 v137, v137, s97, v226
	v_med3_f32 v138, v138, s97, v226
	v_med3_f32 v139, v139, s97, v226
	v_mul_f32_e32 v132, 0xbfb8aa3b, v132
	v_mul_f32_e32 v133, 0xbfb8aa3b, v133
	v_mul_f32_e32 v134, 0xbfb8aa3b, v134
	v_mul_f32_e32 v135, 0xbfb8aa3b, v135
	v_mul_f32_e32 v136, 0xbfb8aa3b, v136
	v_mul_f32_e32 v137, 0xbfb8aa3b, v137
	v_mul_f32_e32 v138, 0xbfb8aa3b, v138
	v_mul_f32_e32 v139, 0xbfb8aa3b, v139
	v_exp_f32_e32 v132, v132
	v_exp_f32_e32 v133, v133
	v_exp_f32_e32 v134, v134
	v_exp_f32_e32 v135, v135
	v_exp_f32_e32 v136, v136
	v_exp_f32_e32 v137, v137
	v_exp_f32_e32 v138, v138
	v_exp_f32_e32 v139, v139
	v_add_f32_e32 v132, 1.0, v132
	v_add_f32_e32 v133, 1.0, v133
	v_add_f32_e32 v134, 1.0, v134
	v_add_f32_e32 v135, 1.0, v135
	v_add_f32_e32 v136, 1.0, v136
	v_add_f32_e32 v137, 1.0, v137
	v_add_f32_e32 v138, 1.0, v138
	v_add_f32_e32 v139, 1.0, v139
	v_rcp_f32_e32 v132, v132
	v_rcp_f32_e32 v133, v133
	v_rcp_f32_e32 v134, v134
	v_rcp_f32_e32 v135, v135
	v_rcp_f32_e32 v136, v136
	v_rcp_f32_e32 v137, v137
	v_rcp_f32_e32 v138, v138
	v_rcp_f32_e32 v139, v139
	v_pk_mul_f32 v[132:133], v[72:73], v[132:133]
	v_pk_mul_f32 v[134:135], v[74:75], v[134:135]
	v_pk_mul_f32 v[136:137], v[68:69], v[136:137]
	v_pk_mul_f32 v[138:139], v[70:71], v[138:139]
	v_cvt_pk_bf16_f32 v248, v132, v133
	v_cvt_pk_bf16_f32 v249, v134, v135
	v_cvt_pk_bf16_f32 v250, v136, v137
	v_cvt_pk_bf16_f32 v251, v138, v139
	s_mov_b64 s[8:9], 0x30000
	v_lshl_add_u64 v[156:157], v[154:155], 0, s[8:9]
	global_store_dwordx4 v[156:157], v[248:251], off offset:256
	s_waitcnt vmcnt(15)
; __device__ __forceinline__ unsigned pk2(float lo, float hi) { f32x2_t v = {lo, hi}; bf16x2_t b = __builtin_convertvector(v, bf16x2_t); return __builtin_bit_cast(unsigned, b); }
;     static __device__ __forceinline__ float e1(float x) { return 1.0f + __expf(-fminf(fmaxf(x, -60.f), 60.f)); }
;     __device__ __forceinline__ void operator()(f32x4 (&acc)[2][2][4][2], const Unit& u, int wr, int wc, int fr, int fq) const {
;     ...
;                     const int col = col0 + bj * HALF;
;                     const bf16_t* gp = proj + (size_t)row * NP + C_GATE + u.z * D + col;
;                     const u32x4 ga = *(const u32x4*)gp;
;                     float sc[8];
;                     { float a[8]; unpack8(ga, a);
; #pragma unroll
;                       for (int j = 0; j < 8; ++j) sc[j] = __builtin_amdgcn_rcpf(e1(a[j])); }
;                     if (u.z < 2) { const u32x4 gb = *(const u32x4*)(gp + D); float b[8]; unpack8(gb, b);
; #pragma unroll
;                       for (int j = 0; j < 8; ++j) sc[j] *= e1(b[j]); }
;                     f32x4 v0 = acc[ai][bj][m][0], v1 = acc[ai][bj][m][1];
;                     v0[0] *= sc[0]; v0[1] *= sc[1]; v0[2] *= sc[2]; v0[3] *= sc[3]; v1[0] *= sc[4]; v1[1] *= sc[5]; v1[2] *= sc[6]; v1[3] *= sc[7];
;                     if (u.z < 2) { acc[ai][bj][m][0] = v0; acc[ai][bj][m][1] = v1; }
;                     else { u32x4 w; w.x = pk2(v0[0], v0[1]); w.y = pk2(v0[2], v0[3]); w.z = pk2(v1[0], v1[1]); w.w = pk2(v1[2], v1[3]); *(u32x4*)(YB + (size_t)row * D + col) = w; }
	v_lshlrev_b32_e32 v132, 16, v162
	v_and_b32_e32 v133, 0xffff0000, v162
	v_lshlrev_b32_e32 v134, 16, v163
	v_and_b32_e32 v135, 0xffff0000, v163
	v_lshlrev_b32_e32 v136, 16, v164
	v_and_b32_e32 v137, 0xffff0000, v164
	v_lshlrev_b32_e32 v138, 16, v165
	v_and_b32_e32 v139, 0xffff0000, v165
	v_max_f32_e32 v132, v132, v132
	v_max_f32_e32 v133, v133, v133
	v_max_f32_e32 v134, v134, v134
	v_max_f32_e32 v135, v135, v135
	v_max_f32_e32 v136, v136, v136
	v_max_f32_e32 v137, v137, v137
	v_max_f32_e32 v138, v138, v138
	v_max_f32_e32 v139, v139, v139
	v_med3_f32 v132, v132, s97, v226
	v_med3_f32 v133, v133, s97, v226
	v_med3_f32 v134, v134, s97, v226
	v_med3_f32 v135, v135, s97, v226
	v_med3_f32 v136, v136, s97, v226
	v_med3_f32 v137, v137, s97, v226
	v_med3_f32 v138, v138, s97, v226
	v_med3_f32 v139, v139, s97, v226
	v_mul_f32_e32 v132, 0xbfb8aa3b, v132
	v_mul_f32_e32 v133, 0xbfb8aa3b, v133
	v_mul_f32_e32 v134, 0xbfb8aa3b, v134
	v_mul_f32_e32 v135, 0xbfb8aa3b, v135
	v_mul_f32_e32 v136, 0xbfb8aa3b, v136
	v_mul_f32_e32 v137, 0xbfb8aa3b, v137
	v_mul_f32_e32 v138, 0xbfb8aa3b, v138
	v_mul_f32_e32 v139, 0xbfb8aa3b, v139
	v_exp_f32_e32 v132, v132
	v_exp_f32_e32 v133, v133
	v_exp_f32_e32 v134, v134
	v_exp_f32_e32 v135, v135
	v_exp_f32_e32 v136, v136
	v_exp_f32_e32 v137, v137
	v_exp_f32_e32 v138, v138
	v_exp_f32_e32 v139, v139
	v_add_f32_e32 v132, 1.0, v132
	v_add_f32_e32 v133, 1.0, v133
	v_add_f32_e32 v134, 1.0, v134
	v_add_f32_e32 v135, 1.0, v135
	v_add_f32_e32 v136, 1.0, v136
	v_add_f32_e32 v137, 1.0, v137
	v_add_f32_e32 v138, 1.0, v138
	v_add_f32_e32 v139, 1.0, v139
	v_rcp_f32_e32 v132, v132
	v_rcp_f32_e32 v133, v133
	v_rcp_f32_e32 v134, v134
	v_rcp_f32_e32 v135, v135
	v_rcp_f32_e32 v136, v136
	v_rcp_f32_e32 v137, v137
	v_rcp_f32_e32 v138, v138
	v_rcp_f32_e32 v139, v139
	v_pk_mul_f32 v[132:133], v[64:65], v[132:133]
	v_pk_mul_f32 v[134:135], v[66:67], v[134:135]
	v_pk_mul_f32 v[136:137], v[60:61], v[136:137]
	v_pk_mul_f32 v[138:139], v[62:63], v[138:139]
	v_cvt_pk_bf16_f32 v244, v132, v133
	v_cvt_pk_bf16_f32 v245, v134, v135
	v_cvt_pk_bf16_f32 v246, v136, v137
	v_cvt_pk_bf16_f32 v247, v138, v139
	s_mov_b64 s[8:9], 0x80000
	v_lshl_add_u64 v[156:157], v[154:155], 0, s[8:9]
	global_store_dwordx4 v[156:157], v[244:247], off offset:0
	s_waitcnt vmcnt(14)
	v_lshlrev_b32_e32 v132, 16, v170
	v_and_b32_e32 v133, 0xffff0000, v170
	v_lshlrev_b32_e32 v134, 16, v171
	v_and_b32_e32 v135, 0xffff0000, v171
	v_lshlrev_b32_e32 v136, 16, v172
	v_and_b32_e32 v137, 0xffff0000, v172
	v_lshlrev_b32_e32 v138, 16, v173
	v_and_b32_e32 v139, 0xffff0000, v173
	v_max_f32_e32 v132, v132, v132
	v_max_f32_e32 v133, v133, v133
	v_max_f32_e32 v134, v134, v134
	v_max_f32_e32 v135, v135, v135
	v_max_f32_e32 v136, v136, v136
	v_max_f32_e32 v137, v137, v137
	v_max_f32_e32 v138, v138, v138
	v_max_f32_e32 v139, v139, v139
	v_med3_f32 v132, v132, s97, v226
	v_med3_f32 v133, v133, s97, v226
	v_med3_f32 v134, v134, s97, v226
	v_med3_f32 v135, v135, s97, v226
	v_med3_f32 v136, v136, s97, v226
	v_med3_f32 v137, v137, s97, v226
	v_med3_f32 v138, v138, s97, v226
	v_med3_f32 v139, v139, s97, v226
	v_mul_f32_e32 v132, 0xbfb8aa3b, v132
	v_mul_f32_e32 v133, 0xbfb8aa3b, v133
	v_mul_f32_e32 v134, 0xbfb8aa3b, v134
	v_mul_f32_e32 v135, 0xbfb8aa3b, v135
	v_mul_f32_e32 v136, 0xbfb8aa3b, v136
	v_mul_f32_e32 v137, 0xbfb8aa3b, v137
	v_mul_f32_e32 v138, 0xbfb8aa3b, v138
	v_mul_f32_e32 v139, 0xbfb8aa3b, v139
	v_exp_f32_e32 v132, v132
	v_exp_f32_e32 v133, v133
	v_exp_f32_e32 v134, v134
	v_exp_f32_e32 v135, v135
	v_exp_f32_e32 v136, v136
	v_exp_f32_e32 v137, v137
	v_exp_f32_e32 v138, v138
	v_exp_f32_e32 v139, v139
	v_add_f32_e32 v132, 1.0, v132
	v_add_f32_e32 v133, 1.0, v133
	v_add_f32_e32 v134, 1.0, v134
	v_add_f32_e32 v135, 1.0, v135
	v_add_f32_e32 v136, 1.0, v136
	v_add_f32_e32 v137, 1.0, v137
	v_add_f32_e32 v138, 1.0, v138
	v_add_f32_e32 v139, 1.0, v139
	v_rcp_f32_e32 v132, v132
	v_rcp_f32_e32 v133, v133
	v_rcp_f32_e32 v134, v134
	v_rcp_f32_e32 v135, v135
	v_rcp_f32_e32 v136, v136
	v_rcp_f32_e32 v137, v137
	v_rcp_f32_e32 v138, v138
	v_rcp_f32_e32 v139, v139
	v_pk_mul_f32 v[132:133], v[32:33], v[132:133]
	v_pk_mul_f32 v[134:135], v[34:35], v[134:135]
	v_pk_mul_f32 v[136:137], v[28:29], v[136:137]
	v_pk_mul_f32 v[138:139], v[30:31], v[138:139]
	v_cvt_pk_bf16_f32 v248, v132, v133
	v_cvt_pk_bf16_f32 v249, v134, v135
	v_cvt_pk_bf16_f32 v250, v136, v137
	v_cvt_pk_bf16_f32 v251, v138, v139
	s_mov_b64 s[8:9], 0x80000
	v_lshl_add_u64 v[156:157], v[154:155], 0, s[8:9]
	global_store_dwordx4 v[156:157], v[248:251], off offset:256
	s_waitcnt vmcnt(13)
; __device__ __forceinline__ unsigned pk2(float lo, float hi) { f32x2_t v = {lo, hi}; bf16x2_t b = __builtin_convertvector(v, bf16x2_t); return __builtin_bit_cast(unsigned, b); }
;     static __device__ __forceinline__ float e1(float x) { return 1.0f + __expf(-fminf(fmaxf(x, -60.f), 60.f)); }
;     __device__ __forceinline__ void operator()(f32x4 (&acc)[2][2][4][2], const Unit& u, int wr, int wc, int fr, int fq) const {
;     ...
;                     const int col = col0 + bj * HALF;
;                     const bf16_t* gp = proj + (size_t)row * NP + C_GATE + u.z * D + col;
;                     const u32x4 ga = *(const u32x4*)gp;
;                     float sc[8];
;                     { float a[8]; unpack8(ga, a);
; #pragma unroll
;                       for (int j = 0; j < 8; ++j) sc[j] = __builtin_amdgcn_rcpf(e1(a[j])); }
;                     if (u.z < 2) { const u32x4 gb = *(const u32x4*)(gp + D); float b[8]; unpack8(gb, b);
; #pragma unroll
;                       for (int j = 0; j < 8; ++j) sc[j] *= e1(b[j]); }
;                     f32x4 v0 = acc[ai][bj][m][0], v1 = acc[ai][bj][m][1];
;                     v0[0] *= sc[0]; v0[1] *= sc[1]; v0[2] *= sc[2]; v0[3] *= sc[3]; v1[0] *= sc[4]; v1[1] *= sc[5]; v1[2] *= sc[6]; v1[3] *= sc[7];
;                     if (u.z < 2) { acc[ai][bj][m][0] = v0; acc[ai][bj][m][1] = v1; }
;                     else { u32x4 w; w.x = pk2(v0[0], v0[1]); w.y = pk2(v0[2], v0[3]); w.z = pk2(v1[0], v1[1]); w.w = pk2(v1[2], v1[3]); *(u32x4*)(YB + (size_t)row * D + col) = w; }
	v_lshlrev_b32_e32 v132, 16, v178
	v_and_b32_e32 v133, 0xffff0000, v178
	v_lshlrev_b32_e32 v134, 16, v179
	v_and_b32_e32 v135, 0xffff0000, v179
	v_lshlrev_b32_e32 v136, 16, v180
	v_and_b32_e32 v137, 0xffff0000, v180
	v_lshlrev_b32_e32 v138, 16, v181
	v_and_b32_e32 v139, 0xffff0000, v181
	v_max_f32_e32 v132, v132, v132
	v_max_f32_e32 v133, v133, v133
	v_max_f32_e32 v134, v134, v134
	v_max_f32_e32 v135, v135, v135
	v_max_f32_e32 v136, v136, v136
	v_max_f32_e32 v137, v137, v137
	v_max_f32_e32 v138, v138, v138
	v_max_f32_e32 v139, v139, v139
	v_med3_f32 v132, v132, s97, v226
	v_med3_f32 v133, v133, s97, v226
	v_med3_f32 v134, v134, s97, v226
	v_med3_f32 v135, v135, s97, v226
	v_med3_f32 v136, v136, s97, v226
	v_med3_f32 v137, v137, s97, v226
	v_med3_f32 v138, v138, s97, v226
	v_med3_f32 v139, v139, s97, v226
	v_mul_f32_e32 v132, 0xbfb8aa3b, v132
	v_mul_f32_e32 v133, 0xbfb8aa3b, v133
	v_mul_f32_e32 v134, 0xbfb8aa3b, v134
	v_mul_f32_e32 v135, 0xbfb8aa3b, v135
	v_mul_f32_e32 v136, 0xbfb8aa3b, v136
	v_mul_f32_e32 v137, 0xbfb8aa3b, v137
	v_mul_f32_e32 v138, 0xbfb8aa3b, v138
	v_mul_f32_e32 v139, 0xbfb8aa3b, v139
	v_exp_f32_e32 v132, v132
	v_exp_f32_e32 v133, v133
	v_exp_f32_e32 v134, v134
	v_exp_f32_e32 v135, v135
	v_exp_f32_e32 v136, v136
	v_exp_f32_e32 v137, v137
	v_exp_f32_e32 v138, v138
	v_exp_f32_e32 v139, v139
	v_add_f32_e32 v132, 1.0, v132
	v_add_f32_e32 v133, 1.0, v133
	v_add_f32_e32 v134, 1.0, v134
	v_add_f32_e32 v135, 1.0, v135
	v_add_f32_e32 v136, 1.0, v136
	v_add_f32_e32 v137, 1.0, v137
	v_add_f32_e32 v138, 1.0, v138
	v_add_f32_e32 v139, 1.0, v139
	v_rcp_f32_e32 v132, v132
	v_rcp_f32_e32 v133, v133
	v_rcp_f32_e32 v134, v134
	v_rcp_f32_e32 v135, v135
	v_rcp_f32_e32 v136, v136
	v_rcp_f32_e32 v137, v137
	v_rcp_f32_e32 v138, v138
	v_rcp_f32_e32 v139, v139
	v_pk_mul_f32 v[132:133], v[56:57], v[132:133]
	v_pk_mul_f32 v[134:135], v[58:59], v[134:135]
	v_pk_mul_f32 v[136:137], v[52:53], v[136:137]
	v_pk_mul_f32 v[138:139], v[54:55], v[138:139]
	v_cvt_pk_bf16_f32 v244, v132, v133
	v_cvt_pk_bf16_f32 v245, v134, v135
	v_cvt_pk_bf16_f32 v246, v136, v137
	v_cvt_pk_bf16_f32 v247, v138, v139
	s_mov_b64 s[8:9], 0x90000
	v_lshl_add_u64 v[156:157], v[154:155], 0, s[8:9]
	global_store_dwordx4 v[156:157], v[244:247], off offset:0
	s_waitcnt vmcnt(12)
	v_lshlrev_b32_e32 v132, 16, v186
	v_and_b32_e32 v133, 0xffff0000, v186
	v_lshlrev_b32_e32 v134, 16, v187
	v_and_b32_e32 v135, 0xffff0000, v187
	v_lshlrev_b32_e32 v136, 16, v188
	v_and_b32_e32 v137, 0xffff0000, v188
	v_lshlrev_b32_e32 v138, 16, v189
	v_and_b32_e32 v139, 0xffff0000, v189
	v_max_f32_e32 v132, v132, v132
	v_max_f32_e32 v133, v133, v133
	v_max_f32_e32 v134, v134, v134
	v_max_f32_e32 v135, v135, v135
	v_max_f32_e32 v136, v136, v136
	v_max_f32_e32 v137, v137, v137
	v_max_f32_e32 v138, v138, v138
	v_max_f32_e32 v139, v139, v139
	v_med3_f32 v132, v132, s97, v226
	v_med3_f32 v133, v133, s97, v226
	v_med3_f32 v134, v134, s97, v226
	v_med3_f32 v135, v135, s97, v226
	v_med3_f32 v136, v136, s97, v226
	v_med3_f32 v137, v137, s97, v226
	v_med3_f32 v138, v138, s97, v226
	v_med3_f32 v139, v139, s97, v226
	v_mul_f32_e32 v132, 0xbfb8aa3b, v132
	v_mul_f32_e32 v133, 0xbfb8aa3b, v133
	v_mul_f32_e32 v134, 0xbfb8aa3b, v134
	v_mul_f32_e32 v135, 0xbfb8aa3b, v135
	v_mul_f32_e32 v136, 0xbfb8aa3b, v136
	v_mul_f32_e32 v137, 0xbfb8aa3b, v137
	v_mul_f32_e32 v138, 0xbfb8aa3b, v138
	v_mul_f32_e32 v139, 0xbfb8aa3b, v139
	v_exp_f32_e32 v132, v132
	v_exp_f32_e32 v133, v133
	v_exp_f32_e32 v134, v134
	v_exp_f32_e32 v135, v135
	v_exp_f32_e32 v136, v136
	v_exp_f32_e32 v137, v137
	v_exp_f32_e32 v138, v138
	v_exp_f32_e32 v139, v139
	v_add_f32_e32 v132, 1.0, v132
	v_add_f32_e32 v133, 1.0, v133
	v_add_f32_e32 v134, 1.0, v134
	v_add_f32_e32 v135, 1.0, v135
	v_add_f32_e32 v136, 1.0, v136
	v_add_f32_e32 v137, 1.0, v137
	v_add_f32_e32 v138, 1.0, v138
	v_add_f32_e32 v139, 1.0, v139
	v_rcp_f32_e32 v132, v132
	v_rcp_f32_e32 v133, v133
	v_rcp_f32_e32 v134, v134
	v_rcp_f32_e32 v135, v135
	v_rcp_f32_e32 v136, v136
	v_rcp_f32_e32 v137, v137
	v_rcp_f32_e32 v138, v138
	v_rcp_f32_e32 v139, v139
	v_pk_mul_f32 v[132:133], v[24:25], v[132:133]
	v_pk_mul_f32 v[134:135], v[26:27], v[134:135]
	v_pk_mul_f32 v[136:137], v[20:21], v[136:137]
	v_pk_mul_f32 v[138:139], v[22:23], v[138:139]
	v_cvt_pk_bf16_f32 v248, v132, v133
	v_cvt_pk_bf16_f32 v249, v134, v135
	v_cvt_pk_bf16_f32 v250, v136, v137
	v_cvt_pk_bf16_f32 v251, v138, v139
	s_mov_b64 s[8:9], 0x90000
	v_lshl_add_u64 v[156:157], v[154:155], 0, s[8:9]
	global_store_dwordx4 v[156:157], v[248:251], off offset:256
	s_waitcnt vmcnt(11)
; __device__ __forceinline__ unsigned pk2(float lo, float hi) { f32x2_t v = {lo, hi}; bf16x2_t b = __builtin_convertvector(v, bf16x2_t); return __builtin_bit_cast(unsigned, b); }
;     static __device__ __forceinline__ float e1(float x) { return 1.0f + __expf(-fminf(fmaxf(x, -60.f), 60.f)); }
;     __device__ __forceinline__ void operator()(f32x4 (&acc)[2][2][4][2], const Unit& u, int wr, int wc, int fr, int fq) const {
;     ...
;                     const int col = col0 + bj * HALF;
;                     const bf16_t* gp = proj + (size_t)row * NP + C_GATE + u.z * D + col;
;                     const u32x4 ga = *(const u32x4*)gp;
;                     float sc[8];
;                     { float a[8]; unpack8(ga, a);
; #pragma unroll
;                       for (int j = 0; j < 8; ++j) sc[j] = __builtin_amdgcn_rcpf(e1(a[j])); }
;                     if (u.z < 2) { const u32x4 gb = *(const u32x4*)(gp + D); float b[8]; unpack8(gb, b);
; #pragma unroll
;                       for (int j = 0; j < 8; ++j) sc[j] *= e1(b[j]); }
;                     f32x4 v0 = acc[ai][bj][m][0], v1 = acc[ai][bj][m][1];
;                     v0[0] *= sc[0]; v0[1] *= sc[1]; v0[2] *= sc[2]; v0[3] *= sc[3]; v1[0] *= sc[4]; v1[1] *= sc[5]; v1[2] *= sc[6]; v1[3] *= sc[7];
;                     if (u.z < 2) { acc[ai][bj][m][0] = v0; acc[ai][bj][m][1] = v1; }
;                     else { u32x4 w; w.x = pk2(v0[0], v0[1]); w.y = pk2(v0[2], v0[3]); w.z = pk2(v1[0], v1[1]); w.w = pk2(v1[2], v1[3]); *(u32x4*)(YB + (size_t)row * D + col) = w; }
	v_lshlrev_b32_e32 v132, 16, v194
	v_and_b32_e32 v133, 0xffff0000, v194
	v_lshlrev_b32_e32 v134, 16, v195
	v_and_b32_e32 v135, 0xffff0000, v195
	v_lshlrev_b32_e32 v136, 16, v196
	v_and_b32_e32 v137, 0xffff0000, v196
	v_lshlrev_b32_e32 v138, 16, v197
	v_and_b32_e32 v139, 0xffff0000, v197
	v_max_f32_e32 v132, v132, v132
	v_max_f32_e32 v133, v133, v133
	v_max_f32_e32 v134, v134, v134
	v_max_f32_e32 v135, v135, v135
	v_max_f32_e32 v136, v136, v136
	v_max_f32_e32 v137, v137, v137
	v_max_f32_e32 v138, v138, v138
	v_max_f32_e32 v139, v139, v139
	v_med3_f32 v132, v132, s97, v226
	v_med3_f32 v133, v133, s97, v226
	v_med3_f32 v134, v134, s97, v226
	v_med3_f32 v135, v135, s97, v226
	v_med3_f32 v136, v136, s97, v226
	v_med3_f32 v137, v137, s97, v226
	v_med3_f32 v138, v138, s97, v226
	v_med3_f32 v139, v139, s97, v226
	v_mul_f32_e32 v132, 0xbfb8aa3b, v132
	v_mul_f32_e32 v133, 0xbfb8aa3b, v133
	v_mul_f32_e32 v134, 0xbfb8aa3b, v134
	v_mul_f32_e32 v135, 0xbfb8aa3b, v135
	v_mul_f32_e32 v136, 0xbfb8aa3b, v136
	v_mul_f32_e32 v137, 0xbfb8aa3b, v137
	v_mul_f32_e32 v138, 0xbfb8aa3b, v138
	v_mul_f32_e32 v139, 0xbfb8aa3b, v139
	v_exp_f32_e32 v132, v132
	v_exp_f32_e32 v133, v133
	v_exp_f32_e32 v134, v134
	v_exp_f32_e32 v135, v135
	v_exp_f32_e32 v136, v136
	v_exp_f32_e32 v137, v137
	v_exp_f32_e32 v138, v138
	v_exp_f32_e32 v139, v139
	v_add_f32_e32 v132, 1.0, v132
	v_add_f32_e32 v133, 1.0, v133
	v_add_f32_e32 v134, 1.0, v134
	v_add_f32_e32 v135, 1.0, v135
	v_add_f32_e32 v136, 1.0, v136
	v_add_f32_e32 v137, 1.0, v137
	v_add_f32_e32 v138, 1.0, v138
	v_add_f32_e32 v139, 1.0, v139
	v_rcp_f32_e32 v132, v132
	v_rcp_f32_e32 v133, v133
	v_rcp_f32_e32 v134, v134
	v_rcp_f32_e32 v135, v135
	v_rcp_f32_e32 v136, v136
	v_rcp_f32_e32 v137, v137
	v_rcp_f32_e32 v138, v138
	v_rcp_f32_e32 v139, v139
	v_pk_mul_f32 v[132:133], v[48:49], v[132:133]
	v_pk_mul_f32 v[134:135], v[50:51], v[134:135]
	v_pk_mul_f32 v[136:137], v[44:45], v[136:137]
	v_pk_mul_f32 v[138:139], v[46:47], v[138:139]
	v_cvt_pk_bf16_f32 v244, v132, v133
	v_cvt_pk_bf16_f32 v245, v134, v135
	v_cvt_pk_bf16_f32 v246, v136, v137
	v_cvt_pk_bf16_f32 v247, v138, v139
	s_mov_b64 s[8:9], 0xa0000
	v_lshl_add_u64 v[156:157], v[154:155], 0, s[8:9]
	global_store_dwordx4 v[156:157], v[244:247], off offset:0
	s_waitcnt vmcnt(10)
	v_lshlrev_b32_e32 v132, 16, v206
	v_and_b32_e32 v133, 0xffff0000, v206
	v_lshlrev_b32_e32 v134, 16, v207
	v_and_b32_e32 v135, 0xffff0000, v207
	v_lshlrev_b32_e32 v136, 16, v208
	v_and_b32_e32 v137, 0xffff0000, v208
	v_lshlrev_b32_e32 v138, 16, v209
	v_and_b32_e32 v139, 0xffff0000, v209
	v_max_f32_e32 v132, v132, v132
	v_max_f32_e32 v133, v133, v133
	v_max_f32_e32 v134, v134, v134
	v_max_f32_e32 v135, v135, v135
	v_max_f32_e32 v136, v136, v136
	v_max_f32_e32 v137, v137, v137
	v_max_f32_e32 v138, v138, v138
	v_max_f32_e32 v139, v139, v139
	v_med3_f32 v132, v132, s97, v226
	v_med3_f32 v133, v133, s97, v226
	v_med3_f32 v134, v134, s97, v226
	v_med3_f32 v135, v135, s97, v226
	v_med3_f32 v136, v136, s97, v226
	v_med3_f32 v137, v137, s97, v226
	v_med3_f32 v138, v138, s97, v226
	v_med3_f32 v139, v139, s97, v226
	v_mul_f32_e32 v132, 0xbfb8aa3b, v132
	v_mul_f32_e32 v133, 0xbfb8aa3b, v133
	v_mul_f32_e32 v134, 0xbfb8aa3b, v134
	v_mul_f32_e32 v135, 0xbfb8aa3b, v135
	v_mul_f32_e32 v136, 0xbfb8aa3b, v136
	v_mul_f32_e32 v137, 0xbfb8aa3b, v137
	v_mul_f32_e32 v138, 0xbfb8aa3b, v138
	v_mul_f32_e32 v139, 0xbfb8aa3b, v139
	v_exp_f32_e32 v132, v132
	v_exp_f32_e32 v133, v133
	v_exp_f32_e32 v134, v134
	v_exp_f32_e32 v135, v135
	v_exp_f32_e32 v136, v136
	v_exp_f32_e32 v137, v137
	v_exp_f32_e32 v138, v138
	v_exp_f32_e32 v139, v139
	v_add_f32_e32 v132, 1.0, v132
	v_add_f32_e32 v133, 1.0, v133
	v_add_f32_e32 v134, 1.0, v134
	v_add_f32_e32 v135, 1.0, v135
	v_add_f32_e32 v136, 1.0, v136
	v_add_f32_e32 v137, 1.0, v137
	v_add_f32_e32 v138, 1.0, v138
	v_add_f32_e32 v139, 1.0, v139
	v_rcp_f32_e32 v132, v132
	v_rcp_f32_e32 v133, v133
	v_rcp_f32_e32 v134, v134
	v_rcp_f32_e32 v135, v135
	v_rcp_f32_e32 v136, v136
	v_rcp_f32_e32 v137, v137
	v_rcp_f32_e32 v138, v138
	v_rcp_f32_e32 v139, v139
	v_pk_mul_f32 v[132:133], v[16:17], v[132:133]
	v_pk_mul_f32 v[134:135], v[18:19], v[134:135]
	v_pk_mul_f32 v[136:137], v[12:13], v[136:137]
	v_pk_mul_f32 v[138:139], v[14:15], v[138:139]
	v_cvt_pk_bf16_f32 v248, v132, v133
	v_cvt_pk_bf16_f32 v249, v134, v135
	v_cvt_pk_bf16_f32 v250, v136, v137
	v_cvt_pk_bf16_f32 v251, v138, v139
	s_mov_b64 s[8:9], 0xa0000
	v_lshl_add_u64 v[156:157], v[154:155], 0, s[8:9]
	global_store_dwordx4 v[156:157], v[248:251], off offset:256
	s_waitcnt vmcnt(9)
; __device__ __forceinline__ unsigned pk2(float lo, float hi) { f32x2_t v = {lo, hi}; bf16x2_t b = __builtin_convertvector(v, bf16x2_t); return __builtin_bit_cast(unsigned, b); }
;     static __device__ __forceinline__ float e1(float x) { return 1.0f + __expf(-fminf(fmaxf(x, -60.f), 60.f)); }
;     __device__ __forceinline__ void operator()(f32x4 (&acc)[2][2][4][2], const Unit& u, int wr, int wc, int fr, int fq) const {
;     ...
;                     const int col = col0 + bj * HALF;
;                     const bf16_t* gp = proj + (size_t)row * NP + C_GATE + u.z * D + col;
;                     const u32x4 ga = *(const u32x4*)gp;
;                     float sc[8];
;                     { float a[8]; unpack8(ga, a);
; #pragma unroll
;                       for (int j = 0; j < 8; ++j) sc[j] = __builtin_amdgcn_rcpf(e1(a[j])); }
;                     if (u.z < 2) { const u32x4 gb = *(const u32x4*)(gp + D); float b[8]; unpack8(gb, b);
; #pragma unroll
;                       for (int j = 0; j < 8; ++j) sc[j] *= e1(b[j]); }
;                     f32x4 v0 = acc[ai][bj][m][0], v1 = acc[ai][bj][m][1];
;                     v0[0] *= sc[0]; v0[1] *= sc[1]; v0[2] *= sc[2]; v0[3] *= sc[3]; v1[0] *= sc[4]; v1[1] *= sc[5]; v1[2] *= sc[6]; v1[3] *= sc[7];
;                     if (u.z < 2) { acc[ai][bj][m][0] = v0; acc[ai][bj][m][1] = v1; }
;                     else { u32x4 w; w.x = pk2(v0[0], v0[1]); w.y = pk2(v0[2], v0[3]); w.z = pk2(v1[0], v1[1]); w.w = pk2(v1[2], v1[3]); *(u32x4*)(YB + (size_t)row * D + col) = w; }
	v_lshlrev_b32_e32 v132, 16, v228
	v_and_b32_e32 v133, 0xffff0000, v228
	v_lshlrev_b32_e32 v134, 16, v229
	v_and_b32_e32 v135, 0xffff0000, v229
	v_lshlrev_b32_e32 v136, 16, v230
	v_and_b32_e32 v137, 0xffff0000, v230
	v_lshlrev_b32_e32 v138, 16, v231
	v_and_b32_e32 v139, 0xffff0000, v231
	v_max_f32_e32 v132, v132, v132
	v_max_f32_e32 v133, v133, v133
	v_max_f32_e32 v134, v134, v134
	v_max_f32_e32 v135, v135, v135
	v_max_f32_e32 v136, v136, v136
	v_max_f32_e32 v137, v137, v137
	v_max_f32_e32 v138, v138, v138
	v_max_f32_e32 v139, v139, v139
	v_med3_f32 v132, v132, s97, v226
	v_med3_f32 v133, v133, s97, v226
	v_med3_f32 v134, v134, s97, v226
	v_med3_f32 v135, v135, s97, v226
	v_med3_f32 v136, v136, s97, v226
	v_med3_f32 v137, v137, s97, v226
	v_med3_f32 v138, v138, s97, v226
	v_med3_f32 v139, v139, s97, v226
	v_mul_f32_e32 v132, 0xbfb8aa3b, v132
	v_mul_f32_e32 v133, 0xbfb8aa3b, v133
	v_mul_f32_e32 v134, 0xbfb8aa3b, v134
	v_mul_f32_e32 v135, 0xbfb8aa3b, v135
	v_mul_f32_e32 v136, 0xbfb8aa3b, v136
	v_mul_f32_e32 v137, 0xbfb8aa3b, v137
	v_mul_f32_e32 v138, 0xbfb8aa3b, v138
	v_mul_f32_e32 v139, 0xbfb8aa3b, v139
	v_exp_f32_e32 v132, v132
	v_exp_f32_e32 v133, v133
	v_exp_f32_e32 v134, v134
	v_exp_f32_e32 v135, v135
	v_exp_f32_e32 v136, v136
	v_exp_f32_e32 v137, v137
	v_exp_f32_e32 v138, v138
	v_exp_f32_e32 v139, v139
	v_add_f32_e32 v132, 1.0, v132
	v_add_f32_e32 v133, 1.0, v133
	v_add_f32_e32 v134, 1.0, v134
	v_add_f32_e32 v135, 1.0, v135
	v_add_f32_e32 v136, 1.0, v136
	v_add_f32_e32 v137, 1.0, v137
	v_add_f32_e32 v138, 1.0, v138
	v_add_f32_e32 v139, 1.0, v139
	v_rcp_f32_e32 v132, v132
	v_rcp_f32_e32 v133, v133
	v_rcp_f32_e32 v134, v134
	v_rcp_f32_e32 v135, v135
	v_rcp_f32_e32 v136, v136
	v_rcp_f32_e32 v137, v137
	v_rcp_f32_e32 v138, v138
	v_rcp_f32_e32 v139, v139
	v_pk_mul_f32 v[132:133], v[40:41], v[132:133]
	v_pk_mul_f32 v[134:135], v[42:43], v[134:135]
	v_pk_mul_f32 v[136:137], v[36:37], v[136:137]
	v_pk_mul_f32 v[138:139], v[38:39], v[138:139]
	v_cvt_pk_bf16_f32 v244, v132, v133
	v_cvt_pk_bf16_f32 v245, v134, v135
	v_cvt_pk_bf16_f32 v246, v136, v137
	v_cvt_pk_bf16_f32 v247, v138, v139
	s_mov_b64 s[8:9], 0xb0000
	v_lshl_add_u64 v[156:157], v[154:155], 0, s[8:9]
	global_store_dwordx4 v[156:157], v[244:247], off offset:0
	s_waitcnt vmcnt(8)
	v_lshlrev_b32_e32 v132, 16, v236
	v_and_b32_e32 v133, 0xffff0000, v236
	v_lshlrev_b32_e32 v134, 16, v237
	v_and_b32_e32 v135, 0xffff0000, v237
	v_lshlrev_b32_e32 v136, 16, v238
	v_and_b32_e32 v137, 0xffff0000, v238
	v_lshlrev_b32_e32 v138, 16, v239
	v_and_b32_e32 v139, 0xffff0000, v239
	v_max_f32_e32 v132, v132, v132
	v_max_f32_e32 v133, v133, v133
	v_max_f32_e32 v134, v134, v134
	v_max_f32_e32 v135, v135, v135
	v_max_f32_e32 v136, v136, v136
	v_max_f32_e32 v137, v137, v137
	v_max_f32_e32 v138, v138, v138
	v_max_f32_e32 v139, v139, v139
	v_med3_f32 v132, v132, s97, v226
	v_med3_f32 v133, v133, s97, v226
	v_med3_f32 v134, v134, s97, v226
	v_med3_f32 v135, v135, s97, v226
	v_med3_f32 v136, v136, s97, v226
	v_med3_f32 v137, v137, s97, v226
	v_med3_f32 v138, v138, s97, v226
	v_med3_f32 v139, v139, s97, v226
	v_mul_f32_e32 v132, 0xbfb8aa3b, v132
	v_mul_f32_e32 v133, 0xbfb8aa3b, v133
	v_mul_f32_e32 v134, 0xbfb8aa3b, v134
	v_mul_f32_e32 v135, 0xbfb8aa3b, v135
	v_mul_f32_e32 v136, 0xbfb8aa3b, v136
	v_mul_f32_e32 v137, 0xbfb8aa3b, v137
	v_mul_f32_e32 v138, 0xbfb8aa3b, v138
	v_mul_f32_e32 v139, 0xbfb8aa3b, v139
	v_exp_f32_e32 v132, v132
	v_exp_f32_e32 v133, v133
	v_exp_f32_e32 v134, v134
	v_exp_f32_e32 v135, v135
	v_exp_f32_e32 v136, v136
	v_exp_f32_e32 v137, v137
	v_exp_f32_e32 v138, v138
	v_exp_f32_e32 v139, v139
	v_add_f32_e32 v132, 1.0, v132
	v_add_f32_e32 v133, 1.0, v133
	v_add_f32_e32 v134, 1.0, v134
	v_add_f32_e32 v135, 1.0, v135
	v_add_f32_e32 v136, 1.0, v136
	v_add_f32_e32 v137, 1.0, v137
	v_add_f32_e32 v138, 1.0, v138
	v_add_f32_e32 v139, 1.0, v139
	v_rcp_f32_e32 v132, v132
	v_rcp_f32_e32 v133, v133
	v_rcp_f32_e32 v134, v134
	v_rcp_f32_e32 v135, v135
	v_rcp_f32_e32 v136, v136
	v_rcp_f32_e32 v137, v137
	v_rcp_f32_e32 v138, v138
	v_rcp_f32_e32 v139, v139
	v_pk_mul_f32 v[132:133], v[8:9], v[132:133]
	v_pk_mul_f32 v[134:135], v[10:11], v[134:135]
	v_pk_mul_f32 v[136:137], v[4:5], v[136:137]
	v_pk_mul_f32 v[138:139], v[6:7], v[138:139]
	v_cvt_pk_bf16_f32 v248, v132, v133
	v_cvt_pk_bf16_f32 v249, v134, v135
	v_cvt_pk_bf16_f32 v250, v136, v137
	v_cvt_pk_bf16_f32 v251, v138, v139
	s_mov_b64 s[8:9], 0xb0000
	v_lshl_add_u64 v[156:157], v[154:155], 0, s[8:9]
	global_store_dwordx4 v[156:157], v[248:251], off offset:256
	s_mov_b64 s[40:41], 0
	s_mov_b64 s[42:43], -1
.Lp3_done:
	s_and_b64 vcc, exec, s[38:39]
	s_mov_b64 s[28:29], -1
	s_cbranch_vccnz .LBB0_607
